# EpiRes epilogues (phases 7,12,15): per-group Vprev/stats loads hoisted behind each half's initial batch, chained addresses, counted waits
# baseline (speedup 1.0000x reference)
.LBB0_889:
	s_cmp_gt_i32 s33, 31
	v_lshl_add_u32 v184, s33, 8, v147
	v_lshl_or_b32 v128, s59, 8, v194
	s_cselect_b32 s24, 0xc000, 0
	v_ashrrev_i32_e32 v185, 31, v184
	s_add_u32 s24, s45, s24
	v_ashrrev_i32_e32 v129, 31, v128
	v_lshlrev_b64 v[166:167], 12, v[184:185]
	s_addc_u32 s25, s50, 0
	v_lshlrev_b64 v[130:131], 2, v[128:129]
	v_lshl_add_u64 v[132:133], s[10:11], 0, v[166:167]
	v_lshlrev_b64 v[182:183], 1, v[128:129]
	v_lshl_add_u64 v[170:171], s[24:25], 0, v[130:131]
	v_lshl_add_u64 v[178:179], v[132:133], 0, v[182:183]
	global_load_dwordx4 v[198:201], v[170:171], off offset:16
	global_load_dwordx4 v[188:191], v[170:171], off
	global_load_dwordx4 v[202:205], v[178:179], off
	v_lshl_add_u64 v[180:181], v[184:185], 3, s[12:13]
	global_load_dwordx2 v[206:207], v[180:181], off
	v_lshl_add_u64 v[176:177], s[48:49], 0, v[130:131]
	v_lshl_add_u64 v[174:175], s[46:47], 0, v[130:131]
	global_load_dwordx4 v[132:135], v[176:177], off
	global_load_dwordx4 v[136:139], v[174:175], off
	global_load_dwordx4 v[128:131], v[174:175], off offset:16
	global_load_dwordx4 v[140:143], v[176:177], off offset:16
	s_mov_b32 s86, 0x10000
	s_mov_b32 s87, 0
	s_mov_b32 s88, 0x50000
	s_mov_b32 s89, 0
	v_lshl_add_u64 v[210:211], v[178:179], 0, s[86:87]
	global_load_dwordx4 v[212:215], v[210:211], off
	v_lshl_add_u64 v[210:211], v[210:211], 0, s[86:87]
	global_load_dwordx4 v[216:219], v[210:211], off
	v_lshl_add_u64 v[210:211], v[210:211], 0, s[86:87]
	global_load_dwordx4 v[220:223], v[210:211], off
	v_lshl_add_u64 v[210:211], v[210:211], 0, s[88:89]
	global_load_dwordx4 v[224:227], v[210:211], off
	v_lshl_add_u64 v[210:211], v[210:211], 0, s[86:87]
	global_load_dwordx4 v[228:231], v[210:211], off
	v_lshl_add_u64 v[210:211], v[210:211], 0, s[86:87]
	global_load_dwordx4 v[232:235], v[210:211], off
	v_lshl_add_u64 v[210:211], v[210:211], 0, s[86:87]
	global_load_dwordx4 v[236:239], v[210:211], off
	global_load_dwordx2 v[240:241], v[180:181], off offset:128
	global_load_dwordx2 v[242:243], v[180:181], off offset:256
	global_load_dwordx2 v[244:245], v[180:181], off offset:384
	global_load_dwordx2 v[246:247], v[180:181], off offset:1024
	global_load_dwordx2 v[250:251], v[180:181], off offset:1152
	global_load_dwordx2 v[252:253], v[180:181], off offset:1280
	global_load_dwordx2 v[254:255], v[180:181], off offset:1408
	v_or_b32_e32 v168, 16, v184
	v_ashrrev_i32_e32 v169, 31, v168
	v_lshl_add_u64 v[172:173], s[14:15], 0, v[166:167]
	v_lshlrev_b64 v[208:209], 12, v[168:169]
	v_lshl_add_u64 v[166:167], v[168:169], 3, s[12:13]
	v_lshl_add_u64 v[168:169], v[172:173], 0, v[182:183]
	v_lshl_add_u64 v[172:173], s[10:11], 0, v[208:209]
	v_lshl_add_u64 v[172:173], v[172:173], 0, v[182:183]
	s_and_b64 vcc, exec, s[0:1]
	s_mov_b64 s[0:1], -1
	s_waitcnt vmcnt(14)
	v_pk_add_f32 v[192:193], v[198:199], 1.0 op_sel_hi:[1,0]
	v_pk_add_f32 v[186:187], v[190:191], 1.0 op_sel_hi:[1,0]
	v_pk_add_f32 v[190:191], v[200:201], 1.0 op_sel_hi:[1,0]
	v_lshlrev_b32_e32 v198, 16, v202
	v_and_b32_e32 v199, 0xffff0000, v202
	v_lshlrev_b32_e32 v200, 16, v203
	v_and_b32_e32 v201, 0xffff0000, v203
	v_lshlrev_b32_e32 v202, 16, v204
	v_and_b32_e32 v203, 0xffff0000, v204
	v_lshlrev_b32_e32 v204, 16, v205
	v_and_b32_e32 v205, 0xffff0000, v205
	v_pk_add_f32 v[198:199], v[198:199], v[206:207] op_sel_hi:[1,0] neg_lo:[0,1] neg_hi:[0,1]
	v_pk_add_f32 v[200:201], v[200:201], v[206:207] op_sel_hi:[1,0] neg_lo:[0,1] neg_hi:[0,1]
	v_pk_add_f32 v[202:203], v[202:203], v[206:207] op_sel_hi:[1,0] neg_lo:[0,1] neg_hi:[0,1]
	v_pk_add_f32 v[204:205], v[204:205], v[206:207] op_sel_hi:[1,0] neg_lo:[0,1] neg_hi:[0,1]
	v_pk_add_f32 v[188:189], v[188:189], 1.0 op_sel_hi:[1,0]
	v_pk_mul_f32 v[198:199], v[206:207], v[198:199] op_sel:[1,0]
	v_pk_mul_f32 v[200:201], v[206:207], v[200:201] op_sel:[1,0]
	v_pk_mul_f32 v[202:203], v[206:207], v[202:203] op_sel:[1,0]
	v_pk_mul_f32 v[204:205], v[206:207], v[204:205] op_sel:[1,0]
	v_pk_mul_f32 v[126:127], v[126:127], v[186:187]
	v_pk_mul_f32 v[124:125], v[124:125], v[188:189]
	v_pk_mul_f32 v[122:123], v[122:123], v[190:191]
	v_pk_mul_f32 v[120:121], v[120:121], v[192:193]
	v_pk_fma_f32 v[198:199], v[136:137], v[198:199], v[132:133]
	v_pk_fma_f32 v[200:201], v[138:139], v[200:201], v[134:135]
	v_pk_fma_f32 v[202:203], v[128:129], v[202:203], v[140:141]
	v_pk_fma_f32 v[204:205], v[130:131], v[204:205], v[142:143]
	v_pk_fma_f32 v[124:125], v[198:199], s[20:21], v[124:125] op_sel_hi:[1,0,1]
	v_pk_fma_f32 v[126:127], v[200:201], s[20:21], v[126:127] op_sel_hi:[1,0,1]
	v_pk_fma_f32 v[202:203], v[202:203], s[20:21], v[120:121] op_sel_hi:[1,0,1]
	v_pk_fma_f32 v[204:205], v[204:205], s[20:21], v[122:123] op_sel_hi:[1,0,1]
	v_cvt_pk_bf16_f32 v120, v124, v125
	v_cvt_pk_bf16_f32 v121, v126, v127
	v_cvt_pk_bf16_f32 v122, v202, v203
	v_cvt_pk_bf16_f32 v123, v204, v205
	v_pk_mul_f32 v[118:119], v[118:119], v[186:187]
	global_store_dwordx4 v[168:169], v[120:123], off
	v_pk_mul_f32 v[116:117], v[116:117], v[188:189]
	s_nop 1
	v_or_b32_e32 v122, 32, v184
	v_ashrrev_i32_e32 v123, 31, v122
	v_lshlrev_b64 v[202:203], 12, v[122:123]
	v_pk_mul_f32 v[114:115], v[114:115], v[190:191]
	v_pk_mul_f32 v[112:113], v[112:113], v[192:193]
	v_lshl_add_u64 v[120:121], v[122:123], 3, s[12:13]
	v_lshl_add_u64 v[122:123], s[14:15], 0, v[208:209]
	v_lshl_add_u64 v[124:125], s[10:11], 0, v[202:203]
	v_lshl_add_u64 v[122:123], v[122:123], 0, v[182:183]
	v_lshl_add_u64 v[124:125], v[124:125], 0, v[182:183]
	v_pk_mul_f32 v[110:111], v[110:111], v[186:187]
	v_pk_mul_f32 v[108:109], v[108:109], v[188:189]
	v_pk_mul_f32 v[106:107], v[106:107], v[190:191]
	v_pk_mul_f32 v[104:105], v[104:105], v[192:193]
	v_pk_mul_f32 v[102:103], v[102:103], v[186:187]
	v_pk_mul_f32 v[100:101], v[100:101], v[188:189]
	v_pk_mul_f32 v[98:99], v[98:99], v[190:191]
	v_pk_mul_f32 v[96:97], v[96:97], v[192:193]
	v_pk_mul_f32 v[94:95], v[94:95], v[186:187]
	v_pk_mul_f32 v[92:93], v[92:93], v[188:189]
	v_pk_mul_f32 v[90:91], v[90:91], v[190:191]
	v_pk_mul_f32 v[88:89], v[88:89], v[192:193]
	v_pk_mul_f32 v[86:87], v[86:87], v[186:187]
	v_pk_mul_f32 v[84:85], v[84:85], v[188:189]
	v_pk_mul_f32 v[82:83], v[82:83], v[190:191]
	v_pk_mul_f32 v[80:81], v[80:81], v[192:193]
	v_pk_mul_f32 v[78:79], v[78:79], v[186:187]
	v_pk_mul_f32 v[76:77], v[76:77], v[188:189]
	v_pk_mul_f32 v[74:75], v[74:75], v[190:191]
	v_pk_mul_f32 v[72:73], v[72:73], v[192:193]
	v_pk_mul_f32 v[70:71], v[70:71], v[186:187]
	v_pk_mul_f32 v[68:69], v[68:69], v[188:189]
	v_pk_mul_f32 v[66:67], v[66:67], v[190:191]
	v_pk_mul_f32 v[64:65], v[64:65], v[192:193]
	s_waitcnt vmcnt(14)
	v_lshlrev_b32_e32 v204, 16, v212
	v_and_b32_e32 v205, 0xffff0000, v212
	v_lshlrev_b32_e32 v198, 16, v213
	v_and_b32_e32 v199, 0xffff0000, v213
	v_lshlrev_b32_e32 v206, 16, v214
	v_and_b32_e32 v207, 0xffff0000, v214
	v_lshlrev_b32_e32 v200, 16, v215
	v_and_b32_e32 v201, 0xffff0000, v215
	s_waitcnt vmcnt(7)
	v_pk_add_f32 v[204:205], v[204:205], v[240:241] op_sel_hi:[1,0] neg_lo:[0,1] neg_hi:[0,1]
	v_pk_add_f32 v[198:199], v[198:199], v[240:241] op_sel_hi:[1,0] neg_lo:[0,1] neg_hi:[0,1]
	v_pk_add_f32 v[206:207], v[206:207], v[240:241] op_sel_hi:[1,0] neg_lo:[0,1] neg_hi:[0,1]
	v_pk_add_f32 v[200:201], v[200:201], v[240:241] op_sel_hi:[1,0] neg_lo:[0,1] neg_hi:[0,1]
	v_pk_mul_f32 v[204:205], v[240:241], v[204:205] op_sel:[1,0]
	v_pk_mul_f32 v[198:199], v[240:241], v[198:199] op_sel:[1,0]
	v_pk_mul_f32 v[206:207], v[240:241], v[206:207] op_sel:[1,0]
	v_pk_mul_f32 v[126:127], v[240:241], v[200:201] op_sel:[1,0]
	v_pk_fma_f32 v[200:201], v[136:137], v[204:205], v[132:133]
	v_pk_fma_f32 v[198:199], v[138:139], v[198:199], v[134:135]
	v_pk_fma_f32 v[204:205], v[128:129], v[206:207], v[140:141]
	v_pk_fma_f32 v[126:127], v[130:131], v[126:127], v[142:143]
	v_pk_fma_f32 v[116:117], v[200:201], s[20:21], v[116:117] op_sel_hi:[1,0,1]
	v_pk_fma_f32 v[118:119], v[198:199], s[20:21], v[118:119] op_sel_hi:[1,0,1]
	v_pk_fma_f32 v[204:205], v[204:205], s[20:21], v[112:113] op_sel_hi:[1,0,1]
	v_pk_fma_f32 v[126:127], v[126:127], s[20:21], v[114:115] op_sel_hi:[1,0,1]
	v_cvt_pk_bf16_f32 v112, v116, v117
	v_cvt_pk_bf16_f32 v113, v118, v119
	v_cvt_pk_bf16_f32 v114, v204, v205
	v_cvt_pk_bf16_f32 v115, v126, v127
	s_nop 0
	global_store_dwordx4 v[122:123], v[112:115], off
	s_waitcnt vmcnt(8)
	v_lshlrev_b32_e32 v204, 16, v218
	v_or_b32_e32 v114, 48, v184
	v_ashrrev_i32_e32 v115, 31, v114
	v_lshl_add_u64 v[112:113], v[114:115], 3, s[12:13]
	v_lshlrev_b64 v[126:127], 12, v[114:115]
	v_lshl_add_u64 v[114:115], s[14:15], 0, v[202:203]
	v_lshlrev_b32_e32 v202, 16, v216
	v_and_b32_e32 v203, 0xffff0000, v216
	v_lshlrev_b32_e32 v198, 16, v217
	v_and_b32_e32 v199, 0xffff0000, v217
	v_and_b32_e32 v205, 0xffff0000, v218
	v_lshlrev_b32_e32 v200, 16, v219
	v_and_b32_e32 v201, 0xffff0000, v219
	s_waitcnt vmcnt(7)
	v_pk_add_f32 v[202:203], v[202:203], v[242:243] op_sel_hi:[1,0] neg_lo:[0,1] neg_hi:[0,1]
	v_pk_add_f32 v[198:199], v[198:199], v[242:243] op_sel_hi:[1,0] neg_lo:[0,1] neg_hi:[0,1]
	v_pk_add_f32 v[204:205], v[204:205], v[242:243] op_sel_hi:[1,0] neg_lo:[0,1] neg_hi:[0,1]
	v_pk_add_f32 v[200:201], v[200:201], v[242:243] op_sel_hi:[1,0] neg_lo:[0,1] neg_hi:[0,1]
	v_pk_mul_f32 v[202:203], v[242:243], v[202:203] op_sel:[1,0]
	v_pk_mul_f32 v[198:199], v[242:243], v[198:199] op_sel:[1,0]
	v_pk_mul_f32 v[204:205], v[242:243], v[204:205] op_sel:[1,0]
	v_pk_mul_f32 v[118:119], v[242:243], v[200:201] op_sel:[1,0]
	v_pk_fma_f32 v[200:201], v[136:137], v[202:203], v[132:133]
	v_pk_fma_f32 v[198:199], v[138:139], v[198:199], v[134:135]
	v_pk_fma_f32 v[202:203], v[128:129], v[204:205], v[140:141]
	v_pk_fma_f32 v[118:119], v[130:131], v[118:119], v[142:143]
	v_lshl_add_u64 v[116:117], s[10:11], 0, v[126:127]
	v_pk_fma_f32 v[200:201], v[200:201], s[20:21], v[108:109] op_sel_hi:[1,0,1]
	v_pk_fma_f32 v[198:199], v[198:199], s[20:21], v[110:111] op_sel_hi:[1,0,1]
	v_pk_fma_f32 v[202:203], v[202:203], s[20:21], v[104:105] op_sel_hi:[1,0,1]
	v_pk_fma_f32 v[118:119], v[118:119], s[20:21], v[106:107] op_sel_hi:[1,0,1]
	v_lshl_add_u64 v[114:115], v[114:115], 0, v[182:183]
	v_lshl_add_u64 v[116:117], v[116:117], 0, v[182:183]
	v_cvt_pk_bf16_f32 v104, v200, v201
	v_cvt_pk_bf16_f32 v105, v198, v199
	v_cvt_pk_bf16_f32 v106, v202, v203
	v_cvt_pk_bf16_f32 v107, v118, v119
	v_add_u32_e32 v198, 0x80, v184
	global_store_dwordx4 v[114:115], v[104:107], off
	v_ashrrev_i32_e32 v199, 31, v198
	v_lshlrev_b64 v[200:201], 12, v[198:199]
	v_lshl_add_u64 v[104:105], s[14:15], 0, v[126:127]
	v_lshl_add_u64 v[126:127], s[10:11], 0, v[200:201]
	v_lshl_add_u64 v[106:107], v[104:105], 0, v[182:183]
	v_lshl_add_u64 v[104:105], v[126:127], 0, v[182:183]
	s_waitcnt vmcnt(8)
	v_lshlrev_b32_e32 v126, 16, v220
	v_and_b32_e32 v127, 0xffff0000, v220
	v_lshlrev_b32_e32 v108, 16, v221
	v_and_b32_e32 v109, 0xffff0000, v221
	v_lshlrev_b32_e32 v202, 16, v222
	v_and_b32_e32 v203, 0xffff0000, v222
	v_lshlrev_b32_e32 v110, 16, v223
	v_and_b32_e32 v111, 0xffff0000, v223
	s_waitcnt vmcnt(7)
	v_pk_add_f32 v[126:127], v[126:127], v[244:245] op_sel_hi:[1,0] neg_lo:[0,1] neg_hi:[0,1]
	v_pk_add_f32 v[108:109], v[108:109], v[244:245] op_sel_hi:[1,0] neg_lo:[0,1] neg_hi:[0,1]
	v_pk_add_f32 v[202:203], v[202:203], v[244:245] op_sel_hi:[1,0] neg_lo:[0,1] neg_hi:[0,1]
	v_pk_add_f32 v[110:111], v[110:111], v[244:245] op_sel_hi:[1,0] neg_lo:[0,1] neg_hi:[0,1]
	v_pk_mul_f32 v[126:127], v[244:245], v[126:127] op_sel:[1,0]
	v_pk_mul_f32 v[108:109], v[244:245], v[108:109] op_sel:[1,0]
	v_pk_mul_f32 v[202:203], v[244:245], v[202:203] op_sel:[1,0]
	v_pk_mul_f32 v[110:111], v[244:245], v[110:111] op_sel:[1,0]
	v_pk_fma_f32 v[118:119], v[136:137], v[126:127], v[132:133]
	v_pk_fma_f32 v[108:109], v[138:139], v[108:109], v[134:135]
	v_pk_fma_f32 v[126:127], v[128:129], v[202:203], v[140:141]
	v_pk_fma_f32 v[110:111], v[130:131], v[110:111], v[142:143]
	v_pk_fma_f32 v[100:101], v[118:119], s[20:21], v[100:101] op_sel_hi:[1,0,1]
	v_pk_fma_f32 v[102:103], v[108:109], s[20:21], v[102:103] op_sel_hi:[1,0,1]
	v_pk_fma_f32 v[108:109], v[126:127], s[20:21], v[96:97] op_sel_hi:[1,0,1]
	v_pk_fma_f32 v[110:111], v[110:111], s[20:21], v[98:99] op_sel_hi:[1,0,1]
	v_cvt_pk_bf16_f32 v96, v100, v101
	v_cvt_pk_bf16_f32 v97, v102, v103
	v_cvt_pk_bf16_f32 v98, v108, v109
	v_cvt_pk_bf16_f32 v99, v110, v111
	global_store_dwordx4 v[106:107], v[96:99], off
	v_lshl_add_u64 v[100:101], v[198:199], 3, s[12:13]
	v_add_u32_e32 v118, 0x90, v184
	v_ashrrev_i32_e32 v119, 31, v118
	v_lshlrev_b64 v[126:127], 12, v[118:119]
	v_lshl_add_u64 v[96:97], s[14:15], 0, v[200:201]
	v_lshl_add_u64 v[198:199], s[10:11], 0, v[126:127]
	v_lshl_add_u64 v[98:99], v[96:97], 0, v[182:183]
	v_lshl_add_u64 v[96:97], v[198:199], 0, v[182:183]
	s_waitcnt vmcnt(8)
	v_lshlrev_b32_e32 v198, 16, v224
	v_and_b32_e32 v199, 0xffff0000, v224
	v_lshlrev_b32_e32 v108, 16, v225
	v_and_b32_e32 v109, 0xffff0000, v225
	v_lshlrev_b32_e32 v200, 16, v226
	v_and_b32_e32 v201, 0xffff0000, v226
	v_lshlrev_b32_e32 v110, 16, v227
	v_and_b32_e32 v111, 0xffff0000, v227
	s_waitcnt vmcnt(7)
	v_pk_add_f32 v[198:199], v[198:199], v[246:247] op_sel_hi:[1,0] neg_lo:[0,1] neg_hi:[0,1]
	v_pk_add_f32 v[108:109], v[108:109], v[246:247] op_sel_hi:[1,0] neg_lo:[0,1] neg_hi:[0,1]
	v_pk_add_f32 v[200:201], v[200:201], v[246:247] op_sel_hi:[1,0] neg_lo:[0,1] neg_hi:[0,1]
	v_pk_add_f32 v[110:111], v[110:111], v[246:247] op_sel_hi:[1,0] neg_lo:[0,1] neg_hi:[0,1]
	v_pk_mul_f32 v[198:199], v[246:247], v[198:199] op_sel:[1,0]
	v_pk_mul_f32 v[108:109], v[246:247], v[108:109] op_sel:[1,0]
	v_pk_mul_f32 v[200:201], v[246:247], v[200:201] op_sel:[1,0]
	v_pk_mul_f32 v[102:103], v[246:247], v[110:111] op_sel:[1,0]
	v_pk_fma_f32 v[110:111], v[136:137], v[198:199], v[132:133]
	v_pk_fma_f32 v[108:109], v[138:139], v[108:109], v[134:135]
	v_pk_fma_f32 v[198:199], v[128:129], v[200:201], v[140:141]
	v_pk_fma_f32 v[102:103], v[130:131], v[102:103], v[142:143]
	v_pk_fma_f32 v[92:93], v[110:111], s[20:21], v[92:93] op_sel_hi:[1,0,1]
	v_pk_fma_f32 v[94:95], v[108:109], s[20:21], v[94:95] op_sel_hi:[1,0,1]
	v_pk_fma_f32 v[108:109], v[198:199], s[20:21], v[88:89] op_sel_hi:[1,0,1]
	v_pk_fma_f32 v[102:103], v[102:103], s[20:21], v[90:91] op_sel_hi:[1,0,1]
	v_cvt_pk_bf16_f32 v88, v92, v93
	v_cvt_pk_bf16_f32 v89, v94, v95
	v_cvt_pk_bf16_f32 v90, v108, v109
	v_cvt_pk_bf16_f32 v91, v102, v103
	global_store_dwordx4 v[98:99], v[88:91], off
	v_lshl_add_u64 v[92:93], v[118:119], 3, s[12:13]
	v_add_u32_e32 v102, 0xa0, v184
	v_ashrrev_i32_e32 v103, 31, v102
	v_lshlrev_b64 v[118:119], 12, v[102:103]
	v_lshl_add_u64 v[88:89], s[14:15], 0, v[126:127]
	v_lshl_add_u64 v[126:127], s[10:11], 0, v[118:119]
	v_lshl_add_u64 v[90:91], v[88:89], 0, v[182:183]
	v_lshl_add_u64 v[88:89], v[126:127], 0, v[182:183]
	s_waitcnt vmcnt(8)
	v_lshlrev_b32_e32 v126, 16, v228
	v_and_b32_e32 v127, 0xffff0000, v228
	v_lshlrev_b32_e32 v108, 16, v229
	v_and_b32_e32 v109, 0xffff0000, v229
	v_lshlrev_b32_e32 v198, 16, v230
	v_and_b32_e32 v199, 0xffff0000, v230
	v_lshlrev_b32_e32 v110, 16, v231
	v_and_b32_e32 v111, 0xffff0000, v231
	s_waitcnt vmcnt(7)
	v_pk_add_f32 v[126:127], v[126:127], v[250:251] op_sel_hi:[1,0] neg_lo:[0,1] neg_hi:[0,1]
	v_pk_add_f32 v[108:109], v[108:109], v[250:251] op_sel_hi:[1,0] neg_lo:[0,1] neg_hi:[0,1]
	v_pk_add_f32 v[198:199], v[198:199], v[250:251] op_sel_hi:[1,0] neg_lo:[0,1] neg_hi:[0,1]
	v_pk_add_f32 v[110:111], v[110:111], v[250:251] op_sel_hi:[1,0] neg_lo:[0,1] neg_hi:[0,1]
	v_pk_mul_f32 v[126:127], v[250:251], v[126:127] op_sel:[1,0]
	v_pk_mul_f32 v[108:109], v[250:251], v[108:109] op_sel:[1,0]
	v_pk_mul_f32 v[198:199], v[250:251], v[198:199] op_sel:[1,0]
	v_pk_mul_f32 v[94:95], v[250:251], v[110:111] op_sel:[1,0]
	v_pk_fma_f32 v[110:111], v[136:137], v[126:127], v[132:133]
	v_pk_fma_f32 v[108:109], v[138:139], v[108:109], v[134:135]
	v_pk_fma_f32 v[126:127], v[128:129], v[198:199], v[140:141]
	v_pk_fma_f32 v[94:95], v[130:131], v[94:95], v[142:143]
	v_pk_fma_f32 v[84:85], v[110:111], s[20:21], v[84:85] op_sel_hi:[1,0,1]
	v_pk_fma_f32 v[86:87], v[108:109], s[20:21], v[86:87] op_sel_hi:[1,0,1]
	v_pk_fma_f32 v[108:109], v[126:127], s[20:21], v[80:81] op_sel_hi:[1,0,1]
	v_pk_fma_f32 v[94:95], v[94:95], s[20:21], v[82:83] op_sel_hi:[1,0,1]
	v_cvt_pk_bf16_f32 v80, v84, v85
	v_cvt_pk_bf16_f32 v81, v86, v87
	v_cvt_pk_bf16_f32 v82, v108, v109
	v_cvt_pk_bf16_f32 v83, v94, v95
	global_store_dwordx4 v[90:91], v[80:83], off
	v_lshl_add_u64 v[86:87], v[102:103], 3, s[12:13]
	v_add_u32_e32 v94, 0xb0, v184
	v_ashrrev_i32_e32 v95, 31, v94
	v_lshlrev_b64 v[102:103], 12, v[94:95]
	v_lshl_add_u64 v[80:81], s[14:15], 0, v[118:119]
	v_lshl_add_u64 v[118:119], s[10:11], 0, v[102:103]
	v_lshl_add_u64 v[82:83], v[80:81], 0, v[182:183]
	v_lshl_add_u64 v[80:81], v[118:119], 0, v[182:183]
	v_lshl_add_u64 v[94:95], v[94:95], 3, s[12:13]
	s_waitcnt vmcnt(8)
	v_lshlrev_b32_e32 v118, 16, v232
	v_and_b32_e32 v119, 0xffff0000, v232
	v_lshlrev_b32_e32 v108, 16, v233
	v_and_b32_e32 v109, 0xffff0000, v233
	v_lshlrev_b32_e32 v126, 16, v234
	v_and_b32_e32 v127, 0xffff0000, v234
	v_lshlrev_b32_e32 v110, 16, v235
	v_and_b32_e32 v111, 0xffff0000, v235
	s_waitcnt vmcnt(7)
	v_pk_add_f32 v[118:119], v[118:119], v[252:253] op_sel_hi:[1,0] neg_lo:[0,1] neg_hi:[0,1]
	v_pk_add_f32 v[108:109], v[108:109], v[252:253] op_sel_hi:[1,0] neg_lo:[0,1] neg_hi:[0,1]
	v_pk_add_f32 v[126:127], v[126:127], v[252:253] op_sel_hi:[1,0] neg_lo:[0,1] neg_hi:[0,1]
	v_pk_add_f32 v[110:111], v[110:111], v[252:253] op_sel_hi:[1,0] neg_lo:[0,1] neg_hi:[0,1]
	v_pk_mul_f32 v[118:119], v[252:253], v[118:119] op_sel:[1,0]
	v_pk_mul_f32 v[108:109], v[252:253], v[108:109] op_sel:[1,0]
	v_pk_mul_f32 v[126:127], v[252:253], v[126:127] op_sel:[1,0]
	v_pk_mul_f32 v[84:85], v[252:253], v[110:111] op_sel:[1,0]
	v_pk_fma_f32 v[110:111], v[136:137], v[118:119], v[132:133]
	v_pk_fma_f32 v[108:109], v[138:139], v[108:109], v[134:135]
	v_pk_fma_f32 v[118:119], v[128:129], v[126:127], v[140:141]
	v_pk_fma_f32 v[84:85], v[130:131], v[84:85], v[142:143]
	v_pk_fma_f32 v[76:77], v[110:111], s[20:21], v[76:77] op_sel_hi:[1,0,1]
	v_pk_fma_f32 v[78:79], v[108:109], s[20:21], v[78:79] op_sel_hi:[1,0,1]
	v_pk_fma_f32 v[108:109], v[118:119], s[20:21], v[72:73] op_sel_hi:[1,0,1]
	v_pk_fma_f32 v[84:85], v[84:85], s[20:21], v[74:75] op_sel_hi:[1,0,1]
	v_cvt_pk_bf16_f32 v72, v76, v77
	v_cvt_pk_bf16_f32 v73, v78, v79
	v_cvt_pk_bf16_f32 v74, v108, v109
	v_cvt_pk_bf16_f32 v75, v84, v85
	global_store_dwordx4 v[82:83], v[72:75], off
	v_lshl_add_u64 v[78:79], s[14:15], 0, v[102:103]
	v_lshl_add_u64 v[84:85], v[78:79], 0, v[182:183]
	s_waitcnt vmcnt(8)
	v_lshlrev_b32_e32 v78, 16, v236
	v_and_b32_e32 v79, 0xffff0000, v236
	v_lshlrev_b32_e32 v72, 16, v237
	v_and_b32_e32 v73, 0xffff0000, v237
	v_lshlrev_b32_e32 v102, 16, v238
	v_and_b32_e32 v103, 0xffff0000, v238
	v_lshlrev_b32_e32 v74, 16, v239
	v_and_b32_e32 v75, 0xffff0000, v239
	s_waitcnt vmcnt(7)
	v_pk_add_f32 v[78:79], v[78:79], v[254:255] op_sel_hi:[1,0] neg_lo:[0,1] neg_hi:[0,1]
	v_pk_add_f32 v[72:73], v[72:73], v[254:255] op_sel_hi:[1,0] neg_lo:[0,1] neg_hi:[0,1]
	v_pk_add_f32 v[102:103], v[102:103], v[254:255] op_sel_hi:[1,0] neg_lo:[0,1] neg_hi:[0,1]
	v_pk_add_f32 v[74:75], v[74:75], v[254:255] op_sel_hi:[1,0] neg_lo:[0,1] neg_hi:[0,1]
	v_pk_mul_f32 v[78:79], v[254:255], v[78:79] op_sel:[1,0]
	v_pk_mul_f32 v[72:73], v[254:255], v[72:73] op_sel:[1,0]
	v_pk_mul_f32 v[102:103], v[254:255], v[102:103] op_sel:[1,0]
	v_pk_mul_f32 v[74:75], v[254:255], v[74:75] op_sel:[1,0]
	v_pk_fma_f32 v[76:77], v[136:137], v[78:79], v[132:133]
	v_pk_fma_f32 v[72:73], v[138:139], v[72:73], v[134:135]
	v_pk_fma_f32 v[78:79], v[128:129], v[102:103], v[140:141]
	v_pk_fma_f32 v[74:75], v[130:131], v[74:75], v[142:143]
	v_pk_fma_f32 v[68:69], v[76:77], s[20:21], v[68:69] op_sel_hi:[1,0,1]
	v_pk_fma_f32 v[70:71], v[72:73], s[20:21], v[70:71] op_sel_hi:[1,0,1]
	v_pk_fma_f32 v[72:73], v[78:79], s[20:21], v[64:65] op_sel_hi:[1,0,1]
	v_pk_fma_f32 v[74:75], v[74:75], s[20:21], v[66:67] op_sel_hi:[1,0,1]
	v_cvt_pk_bf16_f32 v64, v68, v69
	v_cvt_pk_bf16_f32 v65, v70, v71
	v_cvt_pk_bf16_f32 v66, v72, v73
	v_cvt_pk_bf16_f32 v67, v74, v75
	global_store_dwordx4 v[84:85], v[64:67], off
	global_load_dwordx4 v[108:111], v[170:171], off offset:512
	global_load_dwordx4 v[126:129], v[170:171], off offset:528
	global_load_dwordx4 v[130:133], v[178:179], off offset:256
	global_load_dwordx2 v[134:135], v[180:181], off
	global_load_dwordx4 v[68:71], v[176:177], off offset:512
	global_load_dwordx4 v[72:75], v[174:175], off offset:512
	global_load_dwordx4 v[64:67], v[174:175], off offset:528
	global_load_dwordx4 v[76:79], v[176:177], off offset:528
	v_lshl_add_u64 v[210:211], v[178:179], 0, s[86:87]
	global_load_dwordx4 v[212:215], v[210:211], off offset:256
	v_lshl_add_u64 v[210:211], v[210:211], 0, s[86:87]
	global_load_dwordx4 v[216:219], v[210:211], off offset:256
	v_lshl_add_u64 v[210:211], v[210:211], 0, s[86:87]
	global_load_dwordx4 v[220:223], v[210:211], off offset:256
	v_lshl_add_u64 v[210:211], v[210:211], 0, s[88:89]
	global_load_dwordx4 v[224:227], v[210:211], off offset:256
	v_lshl_add_u64 v[210:211], v[210:211], 0, s[86:87]
	global_load_dwordx4 v[228:231], v[210:211], off offset:256
	v_lshl_add_u64 v[210:211], v[210:211], 0, s[86:87]
	global_load_dwordx4 v[232:235], v[210:211], off offset:256
	v_lshl_add_u64 v[210:211], v[210:211], 0, s[86:87]
	global_load_dwordx4 v[236:239], v[210:211], off offset:256
	s_waitcnt vmcnt(14)
	v_pk_add_f32 v[102:103], v[110:111], 1.0 op_sel_hi:[1,0]
	s_waitcnt vmcnt(13)
	v_pk_add_f32 v[110:111], v[128:129], 1.0 op_sel_hi:[1,0]
	v_pk_add_f32 v[118:119], v[126:127], 1.0 op_sel_hi:[1,0]
	s_waitcnt vmcnt(12)
	v_lshlrev_b32_e32 v126, 16, v130
	v_and_b32_e32 v127, 0xffff0000, v130
	v_lshlrev_b32_e32 v128, 16, v131
	v_and_b32_e32 v129, 0xffff0000, v131
	v_lshlrev_b32_e32 v130, 16, v132
	v_and_b32_e32 v131, 0xffff0000, v132
	v_lshlrev_b32_e32 v132, 16, v133
	v_and_b32_e32 v133, 0xffff0000, v133
	s_waitcnt vmcnt(11)
	v_pk_add_f32 v[126:127], v[126:127], v[134:135] op_sel_hi:[1,0] neg_lo:[0,1] neg_hi:[0,1]
	v_pk_add_f32 v[128:129], v[128:129], v[134:135] op_sel_hi:[1,0] neg_lo:[0,1] neg_hi:[0,1]
	v_pk_add_f32 v[130:131], v[130:131], v[134:135] op_sel_hi:[1,0] neg_lo:[0,1] neg_hi:[0,1]
	v_pk_mul_f32 v[138:139], v[56:57], v[118:119]
	v_pk_add_f32 v[56:57], v[132:133], v[134:135] op_sel_hi:[1,0] neg_lo:[0,1] neg_hi:[0,1]
	v_pk_add_f32 v[108:109], v[108:109], 1.0 op_sel_hi:[1,0]
	v_pk_mul_f32 v[136:137], v[58:59], v[110:111]
	v_pk_mul_f32 v[58:59], v[134:135], v[126:127] op_sel:[1,0]
	v_pk_mul_f32 v[126:127], v[134:135], v[128:129] op_sel:[1,0]
	v_pk_mul_f32 v[128:129], v[134:135], v[130:131] op_sel:[1,0]
	v_pk_mul_f32 v[56:57], v[134:135], v[56:57] op_sel:[1,0]
	v_pk_mul_f32 v[62:63], v[62:63], v[102:103]
	v_pk_mul_f32 v[60:61], v[60:61], v[108:109]
	s_waitcnt vmcnt(9)
	v_pk_fma_f32 v[58:59], v[72:73], v[58:59], v[68:69]
	v_pk_fma_f32 v[126:127], v[74:75], v[126:127], v[70:71]
	s_waitcnt vmcnt(7)
	v_pk_fma_f32 v[128:129], v[64:65], v[128:129], v[76:77]
	v_pk_fma_f32 v[130:131], v[66:67], v[56:57], v[78:79]
	v_pk_fma_f32 v[60:61], v[58:59], s[20:21], v[60:61] op_sel_hi:[1,0,1]
	v_pk_fma_f32 v[62:63], v[126:127], s[20:21], v[62:63] op_sel_hi:[1,0,1]
	v_pk_fma_f32 v[126:127], v[128:129], s[20:21], v[138:139] op_sel_hi:[1,0,1]
	v_pk_fma_f32 v[128:129], v[130:131], s[20:21], v[136:137] op_sel_hi:[1,0,1]
	v_cvt_pk_bf16_f32 v60, v60, v61
	v_cvt_pk_bf16_f32 v61, v62, v63
	v_cvt_pk_bf16_f32 v62, v126, v127
	v_cvt_pk_bf16_f32 v63, v128, v129
	v_pk_mul_f32 v[126:127], v[48:49], v[118:119]
	global_store_dwordx4 v[168:169], v[60:63], off offset:256
	v_pk_mul_f32 v[54:55], v[54:55], v[102:103]
	s_nop 1
	v_pk_mul_f32 v[62:63], v[50:51], v[110:111]
	v_pk_mul_f32 v[52:53], v[52:53], v[108:109]
	v_pk_mul_f32 v[46:47], v[46:47], v[102:103]
	v_pk_mul_f32 v[44:45], v[44:45], v[108:109]
	v_pk_mul_f32 v[38:39], v[38:39], v[102:103]
	v_pk_mul_f32 v[36:37], v[36:37], v[108:109]
	v_pk_mul_f32 v[34:35], v[34:35], v[110:111]
	v_pk_mul_f32 v[32:33], v[32:33], v[118:119]
	v_pk_mul_f32 v[30:31], v[30:31], v[102:103]
	v_pk_mul_f32 v[28:29], v[28:29], v[108:109]
	v_pk_mul_f32 v[26:27], v[26:27], v[110:111]
	v_pk_mul_f32 v[24:25], v[24:25], v[118:119]
	v_pk_mul_f32 v[22:23], v[22:23], v[102:103]
	v_pk_mul_f32 v[20:21], v[20:21], v[108:109]
	v_pk_mul_f32 v[18:19], v[18:19], v[110:111]
	v_pk_mul_f32 v[16:17], v[16:17], v[118:119]
	v_pk_mul_f32 v[14:15], v[14:15], v[102:103]
	v_pk_mul_f32 v[12:13], v[12:13], v[108:109]
	v_pk_mul_f32 v[10:11], v[10:11], v[110:111]
	v_pk_mul_f32 v[8:9], v[8:9], v[118:119]
	v_pk_mul_f32 v[6:7], v[6:7], v[102:103]
	v_pk_mul_f32 v[4:5], v[4:5], v[108:109]
	v_pk_mul_f32 v[2:3], v[2:3], v[110:111]
	v_pk_mul_f32 v[0:1], v[0:1], v[118:119]
	s_waitcnt vmcnt(7)
	v_lshlrev_b32_e32 v48, 16, v212
	v_and_b32_e32 v49, 0xffff0000, v212
	v_lshlrev_b32_e32 v50, 16, v213
	v_and_b32_e32 v51, 0xffff0000, v213
	v_lshlrev_b32_e32 v56, 16, v214
	v_and_b32_e32 v57, 0xffff0000, v214
	v_lshlrev_b32_e32 v58, 16, v215
	v_and_b32_e32 v59, 0xffff0000, v215
	s_waitcnt vmcnt(7)
	v_pk_add_f32 v[48:49], v[48:49], v[240:241] op_sel_hi:[1,0] neg_lo:[0,1] neg_hi:[0,1]
	v_pk_add_f32 v[50:51], v[50:51], v[240:241] op_sel_hi:[1,0] neg_lo:[0,1] neg_hi:[0,1]
	v_pk_add_f32 v[56:57], v[56:57], v[240:241] op_sel_hi:[1,0] neg_lo:[0,1] neg_hi:[0,1]
	v_pk_add_f32 v[58:59], v[58:59], v[240:241] op_sel_hi:[1,0] neg_lo:[0,1] neg_hi:[0,1]
	v_pk_mul_f32 v[48:49], v[240:241], v[48:49] op_sel:[1,0]
	v_pk_mul_f32 v[50:51], v[240:241], v[50:51] op_sel:[1,0]
	v_pk_mul_f32 v[56:57], v[240:241], v[56:57] op_sel:[1,0]
	v_pk_mul_f32 v[58:59], v[240:241], v[58:59] op_sel:[1,0]
	v_pk_fma_f32 v[48:49], v[72:73], v[48:49], v[68:69]
	v_pk_fma_f32 v[50:51], v[74:75], v[50:51], v[70:71]
	v_pk_fma_f32 v[56:57], v[64:65], v[56:57], v[76:77]
	v_pk_fma_f32 v[58:59], v[66:67], v[58:59], v[78:79]
	v_pk_fma_f32 v[52:53], v[48:49], s[20:21], v[52:53] op_sel_hi:[1,0,1]
	v_pk_fma_f32 v[54:55], v[50:51], s[20:21], v[54:55] op_sel_hi:[1,0,1]
	v_pk_fma_f32 v[56:57], v[56:57], s[20:21], v[126:127] op_sel_hi:[1,0,1]
	v_pk_fma_f32 v[58:59], v[58:59], s[20:21], v[62:63] op_sel_hi:[1,0,1]
	v_cvt_pk_bf16_f32 v52, v52, v53
	v_cvt_pk_bf16_f32 v53, v54, v55
	v_cvt_pk_bf16_f32 v54, v56, v57
	v_cvt_pk_bf16_f32 v55, v58, v59
	v_pk_mul_f32 v[56:57], v[40:41], v[118:119]
	global_store_dwordx4 v[122:123], v[52:55], off offset:256
	s_waitcnt vmcnt(7)
	v_lshlrev_b32_e32 v40, 16, v216
	v_pk_mul_f32 v[54:55], v[42:43], v[110:111]
	v_and_b32_e32 v41, 0xffff0000, v216
	v_lshlrev_b32_e32 v42, 16, v217
	v_and_b32_e32 v43, 0xffff0000, v217
	v_lshlrev_b32_e32 v48, 16, v218
	v_and_b32_e32 v49, 0xffff0000, v218
	v_lshlrev_b32_e32 v50, 16, v219
	v_and_b32_e32 v51, 0xffff0000, v219
	s_waitcnt vmcnt(7)
	v_pk_add_f32 v[40:41], v[40:41], v[242:243] op_sel_hi:[1,0] neg_lo:[0,1] neg_hi:[0,1]
	v_pk_add_f32 v[42:43], v[42:43], v[242:243] op_sel_hi:[1,0] neg_lo:[0,1] neg_hi:[0,1]
	v_pk_add_f32 v[48:49], v[48:49], v[242:243] op_sel_hi:[1,0] neg_lo:[0,1] neg_hi:[0,1]
	v_pk_add_f32 v[50:51], v[50:51], v[242:243] op_sel_hi:[1,0] neg_lo:[0,1] neg_hi:[0,1]
	v_pk_mul_f32 v[40:41], v[242:243], v[40:41] op_sel:[1,0]
	v_pk_mul_f32 v[42:43], v[242:243], v[42:43] op_sel:[1,0]
	v_pk_mul_f32 v[48:49], v[242:243], v[48:49] op_sel:[1,0]
	v_pk_mul_f32 v[50:51], v[242:243], v[50:51] op_sel:[1,0]
	v_pk_fma_f32 v[40:41], v[72:73], v[40:41], v[68:69]
	v_pk_fma_f32 v[42:43], v[74:75], v[42:43], v[70:71]
	v_pk_fma_f32 v[48:49], v[64:65], v[48:49], v[76:77]
	v_pk_fma_f32 v[50:51], v[66:67], v[50:51], v[78:79]
	v_pk_fma_f32 v[44:45], v[40:41], s[20:21], v[44:45] op_sel_hi:[1,0,1]
	v_pk_fma_f32 v[46:47], v[42:43], s[20:21], v[46:47] op_sel_hi:[1,0,1]
	v_pk_fma_f32 v[48:49], v[48:49], s[20:21], v[56:57] op_sel_hi:[1,0,1]
	v_pk_fma_f32 v[50:51], v[50:51], s[20:21], v[54:55] op_sel_hi:[1,0,1]
	v_cvt_pk_bf16_f32 v44, v44, v45
	v_cvt_pk_bf16_f32 v45, v46, v47
	v_cvt_pk_bf16_f32 v46, v48, v49
	v_cvt_pk_bf16_f32 v47, v50, v51
	s_nop 0
	global_store_dwordx4 v[114:115], v[44:47], off offset:256
	s_waitcnt vmcnt(7)
	v_lshlrev_b32_e32 v48, 16, v222
	v_lshlrev_b32_e32 v46, 16, v220
	v_and_b32_e32 v47, 0xffff0000, v220
	v_lshlrev_b32_e32 v40, 16, v221
	v_and_b32_e32 v41, 0xffff0000, v221
	v_and_b32_e32 v49, 0xffff0000, v222
	v_lshlrev_b32_e32 v42, 16, v223
	v_and_b32_e32 v43, 0xffff0000, v223
	s_waitcnt vmcnt(7)
	v_pk_add_f32 v[46:47], v[46:47], v[244:245] op_sel_hi:[1,0] neg_lo:[0,1] neg_hi:[0,1]
	v_pk_add_f32 v[40:41], v[40:41], v[244:245] op_sel_hi:[1,0] neg_lo:[0,1] neg_hi:[0,1]
	v_pk_add_f32 v[48:49], v[48:49], v[244:245] op_sel_hi:[1,0] neg_lo:[0,1] neg_hi:[0,1]
	v_pk_add_f32 v[42:43], v[42:43], v[244:245] op_sel_hi:[1,0] neg_lo:[0,1] neg_hi:[0,1]
	v_pk_mul_f32 v[46:47], v[244:245], v[46:47] op_sel:[1,0]
	v_pk_mul_f32 v[40:41], v[244:245], v[40:41] op_sel:[1,0]
	v_pk_mul_f32 v[48:49], v[244:245], v[48:49] op_sel:[1,0]
	v_pk_mul_f32 v[42:43], v[244:245], v[42:43] op_sel:[1,0]
	v_pk_fma_f32 v[44:45], v[72:73], v[46:47], v[68:69]
	v_pk_fma_f32 v[40:41], v[74:75], v[40:41], v[70:71]
	v_pk_fma_f32 v[46:47], v[64:65], v[48:49], v[76:77]
	v_pk_fma_f32 v[42:43], v[66:67], v[42:43], v[78:79]
	v_pk_fma_f32 v[36:37], v[44:45], s[20:21], v[36:37] op_sel_hi:[1,0,1]
	v_pk_fma_f32 v[38:39], v[40:41], s[20:21], v[38:39] op_sel_hi:[1,0,1]
	v_pk_fma_f32 v[40:41], v[46:47], s[20:21], v[32:33] op_sel_hi:[1,0,1]
	v_pk_fma_f32 v[42:43], v[42:43], s[20:21], v[34:35] op_sel_hi:[1,0,1]
	v_cvt_pk_bf16_f32 v32, v36, v37
	v_cvt_pk_bf16_f32 v33, v38, v39
	v_cvt_pk_bf16_f32 v34, v40, v41
	v_cvt_pk_bf16_f32 v35, v42, v43
	global_store_dwordx4 v[106:107], v[32:35], off offset:256
	s_nop 0
	s_waitcnt vmcnt(7)
	v_lshlrev_b32_e32 v38, 16, v224
	v_and_b32_e32 v39, 0xffff0000, v224
	v_lshlrev_b32_e32 v32, 16, v225
	v_and_b32_e32 v33, 0xffff0000, v225
	v_lshlrev_b32_e32 v40, 16, v226
	v_and_b32_e32 v41, 0xffff0000, v226
	v_lshlrev_b32_e32 v34, 16, v227
	v_and_b32_e32 v35, 0xffff0000, v227
	s_waitcnt vmcnt(7)
	v_pk_add_f32 v[38:39], v[38:39], v[246:247] op_sel_hi:[1,0] neg_lo:[0,1] neg_hi:[0,1]
	v_pk_add_f32 v[32:33], v[32:33], v[246:247] op_sel_hi:[1,0] neg_lo:[0,1] neg_hi:[0,1]
	v_pk_add_f32 v[40:41], v[40:41], v[246:247] op_sel_hi:[1,0] neg_lo:[0,1] neg_hi:[0,1]
	v_pk_add_f32 v[34:35], v[34:35], v[246:247] op_sel_hi:[1,0] neg_lo:[0,1] neg_hi:[0,1]
	v_pk_mul_f32 v[38:39], v[246:247], v[38:39] op_sel:[1,0]
	v_pk_mul_f32 v[32:33], v[246:247], v[32:33] op_sel:[1,0]
	v_pk_mul_f32 v[40:41], v[246:247], v[40:41] op_sel:[1,0]
	v_pk_mul_f32 v[34:35], v[246:247], v[34:35] op_sel:[1,0]
	v_pk_fma_f32 v[36:37], v[72:73], v[38:39], v[68:69]
	v_pk_fma_f32 v[32:33], v[74:75], v[32:33], v[70:71]
	v_pk_fma_f32 v[38:39], v[64:65], v[40:41], v[76:77]
	v_pk_fma_f32 v[34:35], v[66:67], v[34:35], v[78:79]
	v_pk_fma_f32 v[28:29], v[36:37], s[20:21], v[28:29] op_sel_hi:[1,0,1]
	v_pk_fma_f32 v[30:31], v[32:33], s[20:21], v[30:31] op_sel_hi:[1,0,1]
	v_pk_fma_f32 v[32:33], v[38:39], s[20:21], v[24:25] op_sel_hi:[1,0,1]
	v_pk_fma_f32 v[34:35], v[34:35], s[20:21], v[26:27] op_sel_hi:[1,0,1]
	v_cvt_pk_bf16_f32 v24, v28, v29
	v_cvt_pk_bf16_f32 v25, v30, v31
	v_cvt_pk_bf16_f32 v26, v32, v33
	v_cvt_pk_bf16_f32 v27, v34, v35
	global_store_dwordx4 v[98:99], v[24:27], off offset:256
	s_nop 0
	s_waitcnt vmcnt(7)
	v_lshlrev_b32_e32 v30, 16, v228
	v_and_b32_e32 v31, 0xffff0000, v228
	v_lshlrev_b32_e32 v24, 16, v229
	v_and_b32_e32 v25, 0xffff0000, v229
	v_lshlrev_b32_e32 v32, 16, v230
	v_and_b32_e32 v33, 0xffff0000, v230
	v_lshlrev_b32_e32 v26, 16, v231
	v_and_b32_e32 v27, 0xffff0000, v231
	s_waitcnt vmcnt(7)
	v_pk_add_f32 v[30:31], v[30:31], v[250:251] op_sel_hi:[1,0] neg_lo:[0,1] neg_hi:[0,1]
	v_pk_add_f32 v[24:25], v[24:25], v[250:251] op_sel_hi:[1,0] neg_lo:[0,1] neg_hi:[0,1]
	v_pk_add_f32 v[32:33], v[32:33], v[250:251] op_sel_hi:[1,0] neg_lo:[0,1] neg_hi:[0,1]
	v_pk_add_f32 v[26:27], v[26:27], v[250:251] op_sel_hi:[1,0] neg_lo:[0,1] neg_hi:[0,1]
	v_pk_mul_f32 v[30:31], v[250:251], v[30:31] op_sel:[1,0]
	v_pk_mul_f32 v[24:25], v[250:251], v[24:25] op_sel:[1,0]
	v_pk_mul_f32 v[32:33], v[250:251], v[32:33] op_sel:[1,0]
	v_pk_mul_f32 v[26:27], v[250:251], v[26:27] op_sel:[1,0]
	v_pk_fma_f32 v[28:29], v[72:73], v[30:31], v[68:69]
	v_pk_fma_f32 v[24:25], v[74:75], v[24:25], v[70:71]
	v_pk_fma_f32 v[30:31], v[64:65], v[32:33], v[76:77]
	v_pk_fma_f32 v[26:27], v[66:67], v[26:27], v[78:79]
	v_pk_fma_f32 v[20:21], v[28:29], s[20:21], v[20:21] op_sel_hi:[1,0,1]
	v_pk_fma_f32 v[22:23], v[24:25], s[20:21], v[22:23] op_sel_hi:[1,0,1]
	v_pk_fma_f32 v[24:25], v[30:31], s[20:21], v[16:17] op_sel_hi:[1,0,1]
	v_pk_fma_f32 v[26:27], v[26:27], s[20:21], v[18:19] op_sel_hi:[1,0,1]
	v_cvt_pk_bf16_f32 v16, v20, v21
	v_cvt_pk_bf16_f32 v17, v22, v23
	v_cvt_pk_bf16_f32 v18, v24, v25
	v_cvt_pk_bf16_f32 v19, v26, v27
	global_store_dwordx4 v[90:91], v[16:19], off offset:256
	s_nop 0
	s_waitcnt vmcnt(7)
	v_lshlrev_b32_e32 v22, 16, v232
	v_and_b32_e32 v23, 0xffff0000, v232
	v_lshlrev_b32_e32 v16, 16, v233
	v_and_b32_e32 v17, 0xffff0000, v233
	v_lshlrev_b32_e32 v24, 16, v234
	v_and_b32_e32 v25, 0xffff0000, v234
	v_lshlrev_b32_e32 v18, 16, v235
	v_and_b32_e32 v19, 0xffff0000, v235
	s_waitcnt vmcnt(7)
	v_pk_add_f32 v[22:23], v[22:23], v[252:253] op_sel_hi:[1,0] neg_lo:[0,1] neg_hi:[0,1]
	v_pk_add_f32 v[16:17], v[16:17], v[252:253] op_sel_hi:[1,0] neg_lo:[0,1] neg_hi:[0,1]
	v_pk_add_f32 v[24:25], v[24:25], v[252:253] op_sel_hi:[1,0] neg_lo:[0,1] neg_hi:[0,1]
	v_pk_add_f32 v[18:19], v[18:19], v[252:253] op_sel_hi:[1,0] neg_lo:[0,1] neg_hi:[0,1]
	v_pk_mul_f32 v[22:23], v[252:253], v[22:23] op_sel:[1,0]
	v_pk_mul_f32 v[16:17], v[252:253], v[16:17] op_sel:[1,0]
	v_pk_mul_f32 v[24:25], v[252:253], v[24:25] op_sel:[1,0]
	v_pk_mul_f32 v[18:19], v[252:253], v[18:19] op_sel:[1,0]
	v_pk_fma_f32 v[20:21], v[72:73], v[22:23], v[68:69]
	v_pk_fma_f32 v[16:17], v[74:75], v[16:17], v[70:71]
	v_pk_fma_f32 v[22:23], v[64:65], v[24:25], v[76:77]
	v_pk_fma_f32 v[18:19], v[66:67], v[18:19], v[78:79]
	v_pk_fma_f32 v[12:13], v[20:21], s[20:21], v[12:13] op_sel_hi:[1,0,1]
	v_pk_fma_f32 v[14:15], v[16:17], s[20:21], v[14:15] op_sel_hi:[1,0,1]
	v_pk_fma_f32 v[16:17], v[22:23], s[20:21], v[8:9] op_sel_hi:[1,0,1]
	v_pk_fma_f32 v[18:19], v[18:19], s[20:21], v[10:11] op_sel_hi:[1,0,1]
	v_cvt_pk_bf16_f32 v8, v12, v13
	v_cvt_pk_bf16_f32 v9, v14, v15
	v_cvt_pk_bf16_f32 v10, v16, v17
	v_cvt_pk_bf16_f32 v11, v18, v19
	global_store_dwordx4 v[82:83], v[8:11], off offset:256
	s_nop 0
	s_waitcnt vmcnt(7)
	v_lshlrev_b32_e32 v14, 16, v236
	v_and_b32_e32 v15, 0xffff0000, v236
	v_lshlrev_b32_e32 v8, 16, v237
	v_and_b32_e32 v9, 0xffff0000, v237
	v_lshlrev_b32_e32 v16, 16, v238
	v_and_b32_e32 v17, 0xffff0000, v238
	v_lshlrev_b32_e32 v10, 16, v239
	v_and_b32_e32 v11, 0xffff0000, v239
	s_waitcnt vmcnt(7)
	v_pk_add_f32 v[14:15], v[14:15], v[254:255] op_sel_hi:[1,0] neg_lo:[0,1] neg_hi:[0,1]
	v_pk_add_f32 v[8:9], v[8:9], v[254:255] op_sel_hi:[1,0] neg_lo:[0,1] neg_hi:[0,1]
	v_pk_add_f32 v[16:17], v[16:17], v[254:255] op_sel_hi:[1,0] neg_lo:[0,1] neg_hi:[0,1]
	v_pk_add_f32 v[10:11], v[10:11], v[254:255] op_sel_hi:[1,0] neg_lo:[0,1] neg_hi:[0,1]
	v_pk_mul_f32 v[14:15], v[254:255], v[14:15] op_sel:[1,0]
	v_pk_mul_f32 v[8:9], v[254:255], v[8:9] op_sel:[1,0]
	v_pk_mul_f32 v[16:17], v[254:255], v[16:17] op_sel:[1,0]
	v_pk_mul_f32 v[10:11], v[254:255], v[10:11] op_sel:[1,0]
	v_pk_fma_f32 v[12:13], v[72:73], v[14:15], v[68:69]
	v_pk_fma_f32 v[8:9], v[74:75], v[8:9], v[70:71]
	v_pk_fma_f32 v[14:15], v[64:65], v[16:17], v[76:77]
	v_pk_fma_f32 v[10:11], v[66:67], v[10:11], v[78:79]
	v_pk_fma_f32 v[4:5], v[12:13], s[20:21], v[4:5] op_sel_hi:[1,0,1]
	v_pk_fma_f32 v[6:7], v[8:9], s[20:21], v[6:7] op_sel_hi:[1,0,1]
	v_pk_fma_f32 v[8:9], v[14:15], s[20:21], v[0:1] op_sel_hi:[1,0,1]
	v_pk_fma_f32 v[10:11], v[10:11], s[20:21], v[2:3] op_sel_hi:[1,0,1]
	v_cvt_pk_bf16_f32 v0, v4, v5
	v_cvt_pk_bf16_f32 v1, v6, v7
	v_cvt_pk_bf16_f32 v2, v8, v9
	v_cvt_pk_bf16_f32 v3, v10, v11
	global_store_dwordx4 v[84:85], v[0:3], off offset:256
	s_cbranch_vccnz .LBB0_874
	s_andn2_b64 vcc, exec, s[8:9]
	s_cbranch_vccnz .LBB0_873
	s_barrier
	s_branch .LBB0_873

.LBB0_2425:
	s_cmp_gt_i32 s40, 31
	v_lshl_add_u32 v182, s40, 8, v147
	v_lshl_or_b32 v166, s33, 8, v192
	s_cselect_b32 s25, 0xc000, 0
	v_ashrrev_i32_e32 v183, 31, v182
	s_add_u32 s34, s58, s25
	v_ashrrev_i32_e32 v167, 31, v166
	v_lshlrev_b64 v[168:169], 12, v[182:183]
	s_addc_u32 s35, s59, 0
	v_lshlrev_b64 v[128:129], 2, v[166:167]
	v_lshl_add_u64 v[130:131], s[8:9], 0, v[168:169]
	v_lshlrev_b64 v[180:181], 1, v[166:167]
	v_lshl_add_u64 v[172:173], s[34:35], 0, v[128:129]
	v_lshl_add_u64 v[176:177], v[130:131], 0, v[180:181]
	global_load_dwordx4 v[196:199], v[172:173], off offset:16
	global_load_dwordx4 v[186:189], v[172:173], off
	global_load_dwordx4 v[200:203], v[176:177], off
	v_lshl_add_u64 v[178:179], v[182:183], 3, s[10:11]
	global_load_dwordx2 v[204:205], v[178:179], off
	v_lshl_add_u64 v[130:131], s[12:13], 0, v[128:129]
	v_lshl_add_u64 v[140:141], s[14:15], 0, v[128:129]
	global_load_dwordx4 v[132:135], v[140:141], off
	global_load_dwordx4 v[136:139], v[130:131], off
	s_nop 0
	global_load_dwordx4 v[128:131], v[130:131], off offset:16
	s_nop 0
	global_load_dwordx4 v[140:143], v[140:141], off offset:16
	s_mov_b32 s86, 0x10000
	s_mov_b32 s87, 0
	s_mov_b32 s88, 0x50000
	s_mov_b32 s89, 0
	v_lshl_add_u64 v[208:209], v[176:177], 0, s[86:87]
	global_load_dwordx4 v[210:213], v[208:209], off
	v_lshl_add_u64 v[208:209], v[208:209], 0, s[86:87]
	global_load_dwordx4 v[214:217], v[208:209], off
	v_lshl_add_u64 v[208:209], v[208:209], 0, s[86:87]
	global_load_dwordx4 v[218:221], v[208:209], off
	v_lshl_add_u64 v[208:209], v[208:209], 0, s[88:89]
	global_load_dwordx4 v[222:225], v[208:209], off
	v_lshl_add_u64 v[208:209], v[208:209], 0, s[86:87]
	global_load_dwordx4 v[226:229], v[208:209], off
	v_lshl_add_u64 v[208:209], v[208:209], 0, s[86:87]
	global_load_dwordx4 v[230:233], v[208:209], off
	v_lshl_add_u64 v[208:209], v[208:209], 0, s[86:87]
	global_load_dwordx4 v[234:237], v[208:209], off
	global_load_dwordx2 v[238:239], v[178:179], off offset:128
	global_load_dwordx2 v[240:241], v[178:179], off offset:256
	global_load_dwordx2 v[242:243], v[178:179], off offset:384
	global_load_dwordx2 v[244:245], v[178:179], off offset:1024
	global_load_dwordx2 v[246:247], v[178:179], off offset:1152
	global_load_dwordx2 v[250:251], v[178:179], off offset:1280
	global_load_dwordx2 v[252:253], v[178:179], off offset:1408
	v_or_b32_e32 v170, 16, v182
	v_ashrrev_i32_e32 v171, 31, v170
	v_lshl_add_u64 v[174:175], s[16:17], 0, v[168:169]
	v_lshlrev_b64 v[206:207], 12, v[170:171]
	v_lshl_add_u64 v[168:169], v[170:171], 3, s[10:11]
	v_lshl_add_u64 v[170:171], v[174:175], 0, v[180:181]
	v_lshl_add_u64 v[174:175], s[8:9], 0, v[206:207]
	v_lshl_add_u64 v[174:175], v[174:175], 0, v[180:181]
	s_andn2_b64 vcc, exec, s[0:1]
	s_mov_b64 s[0:1], -1
	s_waitcnt vmcnt(14)
	v_pk_add_f32 v[190:191], v[196:197], 1.0 op_sel_hi:[1,0]
	v_pk_add_f32 v[184:185], v[188:189], 1.0 op_sel_hi:[1,0]
	v_pk_add_f32 v[188:189], v[198:199], 1.0 op_sel_hi:[1,0]
	v_lshlrev_b32_e32 v196, 16, v200
	v_and_b32_e32 v197, 0xffff0000, v200
	v_lshlrev_b32_e32 v198, 16, v201
	v_and_b32_e32 v199, 0xffff0000, v201
	v_lshlrev_b32_e32 v200, 16, v202
	v_and_b32_e32 v201, 0xffff0000, v202
	v_lshlrev_b32_e32 v202, 16, v203
	v_and_b32_e32 v203, 0xffff0000, v203
	v_pk_add_f32 v[196:197], v[196:197], v[204:205] op_sel_hi:[1,0] neg_lo:[0,1] neg_hi:[0,1]
	v_pk_add_f32 v[198:199], v[198:199], v[204:205] op_sel_hi:[1,0] neg_lo:[0,1] neg_hi:[0,1]
	v_pk_add_f32 v[200:201], v[200:201], v[204:205] op_sel_hi:[1,0] neg_lo:[0,1] neg_hi:[0,1]
	v_pk_add_f32 v[202:203], v[202:203], v[204:205] op_sel_hi:[1,0] neg_lo:[0,1] neg_hi:[0,1]
	v_pk_add_f32 v[186:187], v[186:187], 1.0 op_sel_hi:[1,0]
	v_pk_mul_f32 v[196:197], v[204:205], v[196:197] op_sel:[1,0]
	v_pk_mul_f32 v[198:199], v[204:205], v[198:199] op_sel:[1,0]
	v_pk_mul_f32 v[200:201], v[204:205], v[200:201] op_sel:[1,0]
	v_pk_mul_f32 v[202:203], v[204:205], v[202:203] op_sel:[1,0]
	v_pk_mul_f32 v[126:127], v[126:127], v[184:185]
	v_pk_mul_f32 v[124:125], v[124:125], v[186:187]
	v_pk_mul_f32 v[122:123], v[122:123], v[188:189]
	v_pk_mul_f32 v[120:121], v[120:121], v[190:191]
	v_pk_fma_f32 v[196:197], v[136:137], v[196:197], v[132:133]
	v_pk_fma_f32 v[198:199], v[138:139], v[198:199], v[134:135]
	v_pk_fma_f32 v[200:201], v[128:129], v[200:201], v[140:141]
	v_pk_fma_f32 v[202:203], v[130:131], v[202:203], v[142:143]
	v_pk_fma_f32 v[124:125], v[196:197], s[22:23], v[124:125] op_sel_hi:[1,0,1]
	v_pk_fma_f32 v[126:127], v[198:199], s[22:23], v[126:127] op_sel_hi:[1,0,1]
	v_pk_fma_f32 v[200:201], v[200:201], s[22:23], v[120:121] op_sel_hi:[1,0,1]
	v_pk_fma_f32 v[202:203], v[202:203], s[22:23], v[122:123] op_sel_hi:[1,0,1]
	v_cvt_pk_bf16_f32 v120, v124, v125
	v_cvt_pk_bf16_f32 v121, v126, v127
	v_cvt_pk_bf16_f32 v122, v200, v201
	v_cvt_pk_bf16_f32 v123, v202, v203
	v_pk_mul_f32 v[118:119], v[118:119], v[184:185]
	global_store_dwordx4 v[170:171], v[120:123], off
	v_pk_mul_f32 v[116:117], v[116:117], v[186:187]
	s_nop 1
	v_or_b32_e32 v122, 32, v182
	v_ashrrev_i32_e32 v123, 31, v122
	v_lshlrev_b64 v[200:201], 12, v[122:123]
	v_pk_mul_f32 v[114:115], v[114:115], v[188:189]
	v_pk_mul_f32 v[112:113], v[112:113], v[190:191]
	v_lshl_add_u64 v[120:121], v[122:123], 3, s[10:11]
	v_lshl_add_u64 v[122:123], s[16:17], 0, v[206:207]
	v_lshl_add_u64 v[124:125], s[8:9], 0, v[200:201]
	v_lshl_add_u64 v[122:123], v[122:123], 0, v[180:181]
	v_lshl_add_u64 v[124:125], v[124:125], 0, v[180:181]
	v_pk_mul_f32 v[110:111], v[110:111], v[184:185]
	v_pk_mul_f32 v[108:109], v[108:109], v[186:187]
	v_pk_mul_f32 v[106:107], v[106:107], v[188:189]
	v_pk_mul_f32 v[104:105], v[104:105], v[190:191]
	v_pk_mul_f32 v[102:103], v[102:103], v[184:185]
	v_pk_mul_f32 v[100:101], v[100:101], v[186:187]
	v_pk_mul_f32 v[98:99], v[98:99], v[188:189]
	v_pk_mul_f32 v[96:97], v[96:97], v[190:191]
	v_pk_mul_f32 v[94:95], v[94:95], v[184:185]
	v_pk_mul_f32 v[92:93], v[92:93], v[186:187]
	v_pk_mul_f32 v[90:91], v[90:91], v[188:189]
	v_pk_mul_f32 v[88:89], v[88:89], v[190:191]
	v_pk_mul_f32 v[86:87], v[86:87], v[184:185]
	v_pk_mul_f32 v[84:85], v[84:85], v[186:187]
	v_pk_mul_f32 v[82:83], v[82:83], v[188:189]
	v_pk_mul_f32 v[80:81], v[80:81], v[190:191]
	v_pk_mul_f32 v[78:79], v[78:79], v[184:185]
	v_pk_mul_f32 v[76:77], v[76:77], v[186:187]
	v_pk_mul_f32 v[74:75], v[74:75], v[188:189]
	v_pk_mul_f32 v[72:73], v[72:73], v[190:191]
	v_pk_mul_f32 v[70:71], v[70:71], v[184:185]
	v_pk_mul_f32 v[68:69], v[68:69], v[186:187]
	v_pk_mul_f32 v[66:67], v[66:67], v[188:189]
	v_pk_mul_f32 v[64:65], v[64:65], v[190:191]
	s_waitcnt vmcnt(14)
	v_lshlrev_b32_e32 v202, 16, v210
	v_and_b32_e32 v203, 0xffff0000, v210
	v_lshlrev_b32_e32 v196, 16, v211
	v_and_b32_e32 v197, 0xffff0000, v211
	v_lshlrev_b32_e32 v204, 16, v212
	v_and_b32_e32 v205, 0xffff0000, v212
	v_lshlrev_b32_e32 v198, 16, v213
	v_and_b32_e32 v199, 0xffff0000, v213
	s_waitcnt vmcnt(7)
	v_pk_add_f32 v[202:203], v[202:203], v[238:239] op_sel_hi:[1,0] neg_lo:[0,1] neg_hi:[0,1]
	v_pk_add_f32 v[196:197], v[196:197], v[238:239] op_sel_hi:[1,0] neg_lo:[0,1] neg_hi:[0,1]
	v_pk_add_f32 v[204:205], v[204:205], v[238:239] op_sel_hi:[1,0] neg_lo:[0,1] neg_hi:[0,1]
	v_pk_add_f32 v[198:199], v[198:199], v[238:239] op_sel_hi:[1,0] neg_lo:[0,1] neg_hi:[0,1]
	v_pk_mul_f32 v[202:203], v[238:239], v[202:203] op_sel:[1,0]
	v_pk_mul_f32 v[196:197], v[238:239], v[196:197] op_sel:[1,0]
	v_pk_mul_f32 v[204:205], v[238:239], v[204:205] op_sel:[1,0]
	v_pk_mul_f32 v[126:127], v[238:239], v[198:199] op_sel:[1,0]
	v_pk_fma_f32 v[198:199], v[136:137], v[202:203], v[132:133]
	v_pk_fma_f32 v[196:197], v[138:139], v[196:197], v[134:135]
	v_pk_fma_f32 v[202:203], v[128:129], v[204:205], v[140:141]
	v_pk_fma_f32 v[126:127], v[130:131], v[126:127], v[142:143]
	v_pk_fma_f32 v[116:117], v[198:199], s[22:23], v[116:117] op_sel_hi:[1,0,1]
	v_pk_fma_f32 v[118:119], v[196:197], s[22:23], v[118:119] op_sel_hi:[1,0,1]
	v_pk_fma_f32 v[202:203], v[202:203], s[22:23], v[112:113] op_sel_hi:[1,0,1]
	v_pk_fma_f32 v[126:127], v[126:127], s[22:23], v[114:115] op_sel_hi:[1,0,1]
	v_cvt_pk_bf16_f32 v112, v116, v117
	v_cvt_pk_bf16_f32 v113, v118, v119
	v_cvt_pk_bf16_f32 v114, v202, v203
	v_cvt_pk_bf16_f32 v115, v126, v127
	s_nop 0
	global_store_dwordx4 v[122:123], v[112:115], off
	s_waitcnt vmcnt(8)
	v_lshlrev_b32_e32 v202, 16, v216
	v_or_b32_e32 v114, 48, v182
	v_ashrrev_i32_e32 v115, 31, v114
	v_lshl_add_u64 v[112:113], v[114:115], 3, s[10:11]
	v_lshlrev_b64 v[126:127], 12, v[114:115]
	v_lshl_add_u64 v[114:115], s[16:17], 0, v[200:201]
	v_lshlrev_b32_e32 v200, 16, v214
	v_and_b32_e32 v201, 0xffff0000, v214
	v_lshlrev_b32_e32 v196, 16, v215
	v_and_b32_e32 v197, 0xffff0000, v215
	v_and_b32_e32 v203, 0xffff0000, v216
	v_lshlrev_b32_e32 v198, 16, v217
	v_and_b32_e32 v199, 0xffff0000, v217
	s_waitcnt vmcnt(7)
	v_pk_add_f32 v[200:201], v[200:201], v[240:241] op_sel_hi:[1,0] neg_lo:[0,1] neg_hi:[0,1]
	v_pk_add_f32 v[196:197], v[196:197], v[240:241] op_sel_hi:[1,0] neg_lo:[0,1] neg_hi:[0,1]
	v_pk_add_f32 v[202:203], v[202:203], v[240:241] op_sel_hi:[1,0] neg_lo:[0,1] neg_hi:[0,1]
	v_pk_add_f32 v[198:199], v[198:199], v[240:241] op_sel_hi:[1,0] neg_lo:[0,1] neg_hi:[0,1]
	v_pk_mul_f32 v[200:201], v[240:241], v[200:201] op_sel:[1,0]
	v_pk_mul_f32 v[196:197], v[240:241], v[196:197] op_sel:[1,0]
	v_pk_mul_f32 v[202:203], v[240:241], v[202:203] op_sel:[1,0]
	v_pk_mul_f32 v[118:119], v[240:241], v[198:199] op_sel:[1,0]
	v_pk_fma_f32 v[198:199], v[136:137], v[200:201], v[132:133]
	v_pk_fma_f32 v[196:197], v[138:139], v[196:197], v[134:135]
	v_pk_fma_f32 v[200:201], v[128:129], v[202:203], v[140:141]
	v_pk_fma_f32 v[118:119], v[130:131], v[118:119], v[142:143]
	v_lshl_add_u64 v[116:117], s[8:9], 0, v[126:127]
	v_pk_fma_f32 v[198:199], v[198:199], s[22:23], v[108:109] op_sel_hi:[1,0,1]
	v_pk_fma_f32 v[196:197], v[196:197], s[22:23], v[110:111] op_sel_hi:[1,0,1]
	v_pk_fma_f32 v[200:201], v[200:201], s[22:23], v[104:105] op_sel_hi:[1,0,1]
	v_pk_fma_f32 v[118:119], v[118:119], s[22:23], v[106:107] op_sel_hi:[1,0,1]
	v_lshl_add_u64 v[114:115], v[114:115], 0, v[180:181]
	v_lshl_add_u64 v[116:117], v[116:117], 0, v[180:181]
	v_cvt_pk_bf16_f32 v104, v198, v199
	v_cvt_pk_bf16_f32 v105, v196, v197
	v_cvt_pk_bf16_f32 v106, v200, v201
	v_cvt_pk_bf16_f32 v107, v118, v119
	v_add_u32_e32 v196, 0x80, v182
	global_store_dwordx4 v[114:115], v[104:107], off
	v_ashrrev_i32_e32 v197, 31, v196
	v_lshlrev_b64 v[198:199], 12, v[196:197]
	v_lshl_add_u64 v[104:105], s[16:17], 0, v[126:127]
	v_lshl_add_u64 v[126:127], s[8:9], 0, v[198:199]
	v_lshl_add_u64 v[106:107], v[104:105], 0, v[180:181]
	v_lshl_add_u64 v[104:105], v[126:127], 0, v[180:181]
	s_waitcnt vmcnt(8)
	v_lshlrev_b32_e32 v126, 16, v218
	v_and_b32_e32 v127, 0xffff0000, v218
	v_lshlrev_b32_e32 v108, 16, v219
	v_and_b32_e32 v109, 0xffff0000, v219
	v_lshlrev_b32_e32 v200, 16, v220
	v_and_b32_e32 v201, 0xffff0000, v220
	v_lshlrev_b32_e32 v110, 16, v221
	v_and_b32_e32 v111, 0xffff0000, v221
	s_waitcnt vmcnt(7)
	v_pk_add_f32 v[126:127], v[126:127], v[242:243] op_sel_hi:[1,0] neg_lo:[0,1] neg_hi:[0,1]
	v_pk_add_f32 v[108:109], v[108:109], v[242:243] op_sel_hi:[1,0] neg_lo:[0,1] neg_hi:[0,1]
	v_pk_add_f32 v[200:201], v[200:201], v[242:243] op_sel_hi:[1,0] neg_lo:[0,1] neg_hi:[0,1]
	v_pk_add_f32 v[110:111], v[110:111], v[242:243] op_sel_hi:[1,0] neg_lo:[0,1] neg_hi:[0,1]
	v_pk_mul_f32 v[126:127], v[242:243], v[126:127] op_sel:[1,0]
	v_pk_mul_f32 v[108:109], v[242:243], v[108:109] op_sel:[1,0]
	v_pk_mul_f32 v[200:201], v[242:243], v[200:201] op_sel:[1,0]
	v_pk_mul_f32 v[110:111], v[242:243], v[110:111] op_sel:[1,0]
	v_pk_fma_f32 v[118:119], v[136:137], v[126:127], v[132:133]
	v_pk_fma_f32 v[108:109], v[138:139], v[108:109], v[134:135]
	v_pk_fma_f32 v[126:127], v[128:129], v[200:201], v[140:141]
	v_pk_fma_f32 v[110:111], v[130:131], v[110:111], v[142:143]
	v_pk_fma_f32 v[100:101], v[118:119], s[22:23], v[100:101] op_sel_hi:[1,0,1]
	v_pk_fma_f32 v[102:103], v[108:109], s[22:23], v[102:103] op_sel_hi:[1,0,1]
	v_pk_fma_f32 v[108:109], v[126:127], s[22:23], v[96:97] op_sel_hi:[1,0,1]
	v_pk_fma_f32 v[110:111], v[110:111], s[22:23], v[98:99] op_sel_hi:[1,0,1]
	v_cvt_pk_bf16_f32 v96, v100, v101
	v_cvt_pk_bf16_f32 v97, v102, v103
	v_cvt_pk_bf16_f32 v98, v108, v109
	v_cvt_pk_bf16_f32 v99, v110, v111
	global_store_dwordx4 v[106:107], v[96:99], off
	v_lshl_add_u64 v[100:101], v[196:197], 3, s[10:11]
	v_add_u32_e32 v118, 0x90, v182
	v_ashrrev_i32_e32 v119, 31, v118
	v_lshlrev_b64 v[126:127], 12, v[118:119]
	v_lshl_add_u64 v[96:97], s[16:17], 0, v[198:199]
	v_lshl_add_u64 v[196:197], s[8:9], 0, v[126:127]
	v_lshl_add_u64 v[98:99], v[96:97], 0, v[180:181]
	v_lshl_add_u64 v[96:97], v[196:197], 0, v[180:181]
	s_waitcnt vmcnt(8)
	v_lshlrev_b32_e32 v196, 16, v222
	v_and_b32_e32 v197, 0xffff0000, v222
	v_lshlrev_b32_e32 v108, 16, v223
	v_and_b32_e32 v109, 0xffff0000, v223
	v_lshlrev_b32_e32 v198, 16, v224
	v_and_b32_e32 v199, 0xffff0000, v224
	v_lshlrev_b32_e32 v110, 16, v225
	v_and_b32_e32 v111, 0xffff0000, v225
	s_waitcnt vmcnt(7)
	v_pk_add_f32 v[196:197], v[196:197], v[244:245] op_sel_hi:[1,0] neg_lo:[0,1] neg_hi:[0,1]
	v_pk_add_f32 v[108:109], v[108:109], v[244:245] op_sel_hi:[1,0] neg_lo:[0,1] neg_hi:[0,1]
	v_pk_add_f32 v[198:199], v[198:199], v[244:245] op_sel_hi:[1,0] neg_lo:[0,1] neg_hi:[0,1]
	v_pk_add_f32 v[110:111], v[110:111], v[244:245] op_sel_hi:[1,0] neg_lo:[0,1] neg_hi:[0,1]
	v_pk_mul_f32 v[196:197], v[244:245], v[196:197] op_sel:[1,0]
	v_pk_mul_f32 v[108:109], v[244:245], v[108:109] op_sel:[1,0]
	v_pk_mul_f32 v[198:199], v[244:245], v[198:199] op_sel:[1,0]
	v_pk_mul_f32 v[102:103], v[244:245], v[110:111] op_sel:[1,0]
	v_pk_fma_f32 v[110:111], v[136:137], v[196:197], v[132:133]
	v_pk_fma_f32 v[108:109], v[138:139], v[108:109], v[134:135]
	v_pk_fma_f32 v[196:197], v[128:129], v[198:199], v[140:141]
	v_pk_fma_f32 v[102:103], v[130:131], v[102:103], v[142:143]
	v_pk_fma_f32 v[92:93], v[110:111], s[22:23], v[92:93] op_sel_hi:[1,0,1]
	v_pk_fma_f32 v[94:95], v[108:109], s[22:23], v[94:95] op_sel_hi:[1,0,1]
	v_pk_fma_f32 v[108:109], v[196:197], s[22:23], v[88:89] op_sel_hi:[1,0,1]
	v_pk_fma_f32 v[102:103], v[102:103], s[22:23], v[90:91] op_sel_hi:[1,0,1]
	v_cvt_pk_bf16_f32 v88, v92, v93
	v_cvt_pk_bf16_f32 v89, v94, v95
	v_cvt_pk_bf16_f32 v90, v108, v109
	v_cvt_pk_bf16_f32 v91, v102, v103
	global_store_dwordx4 v[98:99], v[88:91], off
	v_lshl_add_u64 v[92:93], v[118:119], 3, s[10:11]
	v_add_u32_e32 v102, 0xa0, v182
	v_ashrrev_i32_e32 v103, 31, v102
	v_lshlrev_b64 v[118:119], 12, v[102:103]
	v_lshl_add_u64 v[88:89], s[16:17], 0, v[126:127]
	v_lshl_add_u64 v[126:127], s[8:9], 0, v[118:119]
	v_lshl_add_u64 v[90:91], v[88:89], 0, v[180:181]
	v_lshl_add_u64 v[88:89], v[126:127], 0, v[180:181]
	s_waitcnt vmcnt(8)
	v_lshlrev_b32_e32 v126, 16, v226
	v_and_b32_e32 v127, 0xffff0000, v226
	v_lshlrev_b32_e32 v108, 16, v227
	v_and_b32_e32 v109, 0xffff0000, v227
	v_lshlrev_b32_e32 v196, 16, v228
	v_and_b32_e32 v197, 0xffff0000, v228
	v_lshlrev_b32_e32 v110, 16, v229
	v_and_b32_e32 v111, 0xffff0000, v229
	s_waitcnt vmcnt(7)
	v_pk_add_f32 v[126:127], v[126:127], v[246:247] op_sel_hi:[1,0] neg_lo:[0,1] neg_hi:[0,1]
	v_pk_add_f32 v[108:109], v[108:109], v[246:247] op_sel_hi:[1,0] neg_lo:[0,1] neg_hi:[0,1]
	v_pk_add_f32 v[196:197], v[196:197], v[246:247] op_sel_hi:[1,0] neg_lo:[0,1] neg_hi:[0,1]
	v_pk_add_f32 v[110:111], v[110:111], v[246:247] op_sel_hi:[1,0] neg_lo:[0,1] neg_hi:[0,1]
	v_pk_mul_f32 v[126:127], v[246:247], v[126:127] op_sel:[1,0]
	v_pk_mul_f32 v[108:109], v[246:247], v[108:109] op_sel:[1,0]
	v_pk_mul_f32 v[196:197], v[246:247], v[196:197] op_sel:[1,0]
	v_pk_mul_f32 v[94:95], v[246:247], v[110:111] op_sel:[1,0]
	v_pk_fma_f32 v[110:111], v[136:137], v[126:127], v[132:133]
	v_pk_fma_f32 v[108:109], v[138:139], v[108:109], v[134:135]
	v_pk_fma_f32 v[126:127], v[128:129], v[196:197], v[140:141]
	v_pk_fma_f32 v[94:95], v[130:131], v[94:95], v[142:143]
	v_pk_fma_f32 v[84:85], v[110:111], s[22:23], v[84:85] op_sel_hi:[1,0,1]
	v_pk_fma_f32 v[86:87], v[108:109], s[22:23], v[86:87] op_sel_hi:[1,0,1]
	v_pk_fma_f32 v[108:109], v[126:127], s[22:23], v[80:81] op_sel_hi:[1,0,1]
	v_pk_fma_f32 v[94:95], v[94:95], s[22:23], v[82:83] op_sel_hi:[1,0,1]
	v_cvt_pk_bf16_f32 v80, v84, v85
	v_cvt_pk_bf16_f32 v81, v86, v87
	v_cvt_pk_bf16_f32 v82, v108, v109
	v_cvt_pk_bf16_f32 v83, v94, v95
	global_store_dwordx4 v[90:91], v[80:83], off
	v_lshl_add_u64 v[86:87], v[102:103], 3, s[10:11]
	v_add_u32_e32 v94, 0xb0, v182
	v_ashrrev_i32_e32 v95, 31, v94
	v_lshlrev_b64 v[102:103], 12, v[94:95]
	v_lshl_add_u64 v[82:83], s[16:17], 0, v[118:119]
	v_lshl_add_u64 v[118:119], s[8:9], 0, v[102:103]
	v_lshl_add_u64 v[84:85], v[82:83], 0, v[180:181]
	v_lshl_add_u64 v[82:83], v[118:119], 0, v[180:181]
	v_lshl_add_u64 v[94:95], v[94:95], 3, s[10:11]
	s_waitcnt vmcnt(8)
	v_lshlrev_b32_e32 v118, 16, v230
	v_and_b32_e32 v119, 0xffff0000, v230
	v_lshlrev_b32_e32 v108, 16, v231
	v_and_b32_e32 v109, 0xffff0000, v231
	v_lshlrev_b32_e32 v126, 16, v232
	v_and_b32_e32 v127, 0xffff0000, v232
	v_lshlrev_b32_e32 v110, 16, v233
	v_and_b32_e32 v111, 0xffff0000, v233
	s_waitcnt vmcnt(7)
	v_pk_add_f32 v[118:119], v[118:119], v[250:251] op_sel_hi:[1,0] neg_lo:[0,1] neg_hi:[0,1]
	v_pk_add_f32 v[108:109], v[108:109], v[250:251] op_sel_hi:[1,0] neg_lo:[0,1] neg_hi:[0,1]
	v_pk_add_f32 v[126:127], v[126:127], v[250:251] op_sel_hi:[1,0] neg_lo:[0,1] neg_hi:[0,1]
	v_pk_add_f32 v[110:111], v[110:111], v[250:251] op_sel_hi:[1,0] neg_lo:[0,1] neg_hi:[0,1]
	v_pk_mul_f32 v[118:119], v[250:251], v[118:119] op_sel:[1,0]
	v_pk_mul_f32 v[108:109], v[250:251], v[108:109] op_sel:[1,0]
	v_pk_mul_f32 v[126:127], v[250:251], v[126:127] op_sel:[1,0]
	v_pk_mul_f32 v[80:81], v[250:251], v[110:111] op_sel:[1,0]
	v_pk_fma_f32 v[110:111], v[136:137], v[118:119], v[132:133]
	v_pk_fma_f32 v[108:109], v[138:139], v[108:109], v[134:135]
	v_pk_fma_f32 v[118:119], v[128:129], v[126:127], v[140:141]
	v_pk_fma_f32 v[80:81], v[130:131], v[80:81], v[142:143]
	v_pk_fma_f32 v[76:77], v[110:111], s[22:23], v[76:77] op_sel_hi:[1,0,1]
	v_pk_fma_f32 v[78:79], v[108:109], s[22:23], v[78:79] op_sel_hi:[1,0,1]
	v_pk_fma_f32 v[108:109], v[118:119], s[22:23], v[72:73] op_sel_hi:[1,0,1]
	v_pk_fma_f32 v[80:81], v[80:81], s[22:23], v[74:75] op_sel_hi:[1,0,1]
	v_cvt_pk_bf16_f32 v72, v76, v77
	v_cvt_pk_bf16_f32 v73, v78, v79
	v_cvt_pk_bf16_f32 v74, v108, v109
	v_cvt_pk_bf16_f32 v75, v80, v81
	global_store_dwordx4 v[84:85], v[72:75], off
	v_lshl_add_u64 v[78:79], s[16:17], 0, v[102:103]
	v_lshl_add_u64 v[80:81], v[78:79], 0, v[180:181]
	s_waitcnt vmcnt(8)
	v_lshlrev_b32_e32 v78, 16, v234
	v_and_b32_e32 v79, 0xffff0000, v234
	v_lshlrev_b32_e32 v72, 16, v235
	v_and_b32_e32 v73, 0xffff0000, v235
	v_lshlrev_b32_e32 v102, 16, v236
	v_and_b32_e32 v103, 0xffff0000, v236
	v_lshlrev_b32_e32 v74, 16, v237
	v_and_b32_e32 v75, 0xffff0000, v237
	s_waitcnt vmcnt(7)
	v_pk_add_f32 v[78:79], v[78:79], v[252:253] op_sel_hi:[1,0] neg_lo:[0,1] neg_hi:[0,1]
	v_pk_add_f32 v[72:73], v[72:73], v[252:253] op_sel_hi:[1,0] neg_lo:[0,1] neg_hi:[0,1]
	v_pk_add_f32 v[102:103], v[102:103], v[252:253] op_sel_hi:[1,0] neg_lo:[0,1] neg_hi:[0,1]
	v_pk_add_f32 v[74:75], v[74:75], v[252:253] op_sel_hi:[1,0] neg_lo:[0,1] neg_hi:[0,1]
	v_pk_mul_f32 v[78:79], v[252:253], v[78:79] op_sel:[1,0]
	v_pk_mul_f32 v[72:73], v[252:253], v[72:73] op_sel:[1,0]
	v_pk_mul_f32 v[102:103], v[252:253], v[102:103] op_sel:[1,0]
	v_pk_mul_f32 v[74:75], v[252:253], v[74:75] op_sel:[1,0]
	v_pk_fma_f32 v[76:77], v[136:137], v[78:79], v[132:133]
	v_pk_fma_f32 v[72:73], v[138:139], v[72:73], v[134:135]
	v_pk_fma_f32 v[78:79], v[128:129], v[102:103], v[140:141]
	v_pk_fma_f32 v[74:75], v[130:131], v[74:75], v[142:143]
	v_pk_fma_f32 v[68:69], v[76:77], s[22:23], v[68:69] op_sel_hi:[1,0,1]
	v_pk_fma_f32 v[70:71], v[72:73], s[22:23], v[70:71] op_sel_hi:[1,0,1]
	v_pk_fma_f32 v[72:73], v[78:79], s[22:23], v[64:65] op_sel_hi:[1,0,1]
	v_pk_fma_f32 v[74:75], v[74:75], s[22:23], v[66:67] op_sel_hi:[1,0,1]
	v_cvt_pk_bf16_f32 v64, v68, v69
	v_cvt_pk_bf16_f32 v65, v70, v71
	v_cvt_pk_bf16_f32 v66, v72, v73
	v_cvt_pk_bf16_f32 v67, v74, v75
	global_store_dwordx4 v[80:81], v[64:67], off
	global_load_dwordx4 v[108:111], v[172:173], off offset:512
	global_load_dwordx4 v[126:129], v[172:173], off offset:528
	global_load_dwordx4 v[130:133], v[176:177], off offset:256
	global_load_dwordx2 v[134:135], v[178:179], off
	v_or_b32_e32 v64, 0x80, v166
	v_ashrrev_i32_e32 v65, 31, v64
	v_lshlrev_b64 v[64:65], 2, v[64:65]
	v_lshl_add_u64 v[66:67], s[12:13], 0, v[64:65]
	v_lshl_add_u64 v[76:77], s[14:15], 0, v[64:65]
	global_load_dwordx4 v[68:71], v[76:77], off
	global_load_dwordx4 v[72:75], v[66:67], off
	s_nop 0
	global_load_dwordx4 v[64:67], v[66:67], off offset:16
	s_nop 0
	global_load_dwordx4 v[76:79], v[76:77], off offset:16
	v_lshl_add_u64 v[208:209], v[176:177], 0, s[86:87]
	global_load_dwordx4 v[210:213], v[208:209], off offset:256
	v_lshl_add_u64 v[208:209], v[208:209], 0, s[86:87]
	global_load_dwordx4 v[214:217], v[208:209], off offset:256
	v_lshl_add_u64 v[208:209], v[208:209], 0, s[86:87]
	global_load_dwordx4 v[218:221], v[208:209], off offset:256
	v_lshl_add_u64 v[208:209], v[208:209], 0, s[88:89]
	global_load_dwordx4 v[222:225], v[208:209], off offset:256
	v_lshl_add_u64 v[208:209], v[208:209], 0, s[86:87]
	global_load_dwordx4 v[226:229], v[208:209], off offset:256
	v_lshl_add_u64 v[208:209], v[208:209], 0, s[86:87]
	global_load_dwordx4 v[230:233], v[208:209], off offset:256
	v_lshl_add_u64 v[208:209], v[208:209], 0, s[86:87]
	global_load_dwordx4 v[234:237], v[208:209], off offset:256
	s_waitcnt vmcnt(14)
	v_pk_add_f32 v[102:103], v[110:111], 1.0 op_sel_hi:[1,0]
	s_waitcnt vmcnt(13)
	v_pk_add_f32 v[110:111], v[128:129], 1.0 op_sel_hi:[1,0]
	v_pk_add_f32 v[118:119], v[126:127], 1.0 op_sel_hi:[1,0]
	s_waitcnt vmcnt(12)
	v_lshlrev_b32_e32 v126, 16, v130
	v_and_b32_e32 v127, 0xffff0000, v130
	v_lshlrev_b32_e32 v128, 16, v131
	v_and_b32_e32 v129, 0xffff0000, v131
	v_lshlrev_b32_e32 v130, 16, v132
	v_and_b32_e32 v131, 0xffff0000, v132
	v_lshlrev_b32_e32 v132, 16, v133
	v_and_b32_e32 v133, 0xffff0000, v133
	s_waitcnt vmcnt(11)
	v_pk_add_f32 v[126:127], v[126:127], v[134:135] op_sel_hi:[1,0] neg_lo:[0,1] neg_hi:[0,1]
	v_pk_add_f32 v[128:129], v[128:129], v[134:135] op_sel_hi:[1,0] neg_lo:[0,1] neg_hi:[0,1]
	v_pk_add_f32 v[130:131], v[130:131], v[134:135] op_sel_hi:[1,0] neg_lo:[0,1] neg_hi:[0,1]
	v_pk_mul_f32 v[138:139], v[56:57], v[118:119]
	v_pk_add_f32 v[56:57], v[132:133], v[134:135] op_sel_hi:[1,0] neg_lo:[0,1] neg_hi:[0,1]
	v_pk_add_f32 v[108:109], v[108:109], 1.0 op_sel_hi:[1,0]
	v_pk_mul_f32 v[136:137], v[58:59], v[110:111]
	v_pk_mul_f32 v[58:59], v[134:135], v[126:127] op_sel:[1,0]
	v_pk_mul_f32 v[126:127], v[134:135], v[128:129] op_sel:[1,0]
	v_pk_mul_f32 v[128:129], v[134:135], v[130:131] op_sel:[1,0]
	v_pk_mul_f32 v[56:57], v[134:135], v[56:57] op_sel:[1,0]
	v_pk_mul_f32 v[62:63], v[62:63], v[102:103]
	v_pk_mul_f32 v[60:61], v[60:61], v[108:109]
	s_waitcnt vmcnt(9)
	v_pk_fma_f32 v[58:59], v[72:73], v[58:59], v[68:69]
	v_pk_fma_f32 v[126:127], v[74:75], v[126:127], v[70:71]
	s_waitcnt vmcnt(7)
	v_pk_fma_f32 v[128:129], v[64:65], v[128:129], v[76:77]
	v_pk_fma_f32 v[130:131], v[66:67], v[56:57], v[78:79]
	v_pk_fma_f32 v[60:61], v[58:59], s[22:23], v[60:61] op_sel_hi:[1,0,1]
	v_pk_fma_f32 v[62:63], v[126:127], s[22:23], v[62:63] op_sel_hi:[1,0,1]
	v_pk_fma_f32 v[126:127], v[128:129], s[22:23], v[138:139] op_sel_hi:[1,0,1]
	v_pk_fma_f32 v[128:129], v[130:131], s[22:23], v[136:137] op_sel_hi:[1,0,1]
	v_cvt_pk_bf16_f32 v60, v60, v61
	v_cvt_pk_bf16_f32 v61, v62, v63
	v_cvt_pk_bf16_f32 v62, v126, v127
	v_cvt_pk_bf16_f32 v63, v128, v129
	v_pk_mul_f32 v[126:127], v[48:49], v[118:119]
	global_store_dwordx4 v[170:171], v[60:63], off offset:256
	v_pk_mul_f32 v[54:55], v[54:55], v[102:103]
	s_nop 1
	v_pk_mul_f32 v[62:63], v[50:51], v[110:111]
	v_pk_mul_f32 v[52:53], v[52:53], v[108:109]
	v_pk_mul_f32 v[46:47], v[46:47], v[102:103]
	v_pk_mul_f32 v[44:45], v[44:45], v[108:109]
	v_pk_mul_f32 v[38:39], v[38:39], v[102:103]
	v_pk_mul_f32 v[36:37], v[36:37], v[108:109]
	v_pk_mul_f32 v[34:35], v[34:35], v[110:111]
	v_pk_mul_f32 v[32:33], v[32:33], v[118:119]
	v_pk_mul_f32 v[30:31], v[30:31], v[102:103]
	v_pk_mul_f32 v[28:29], v[28:29], v[108:109]
	v_pk_mul_f32 v[26:27], v[26:27], v[110:111]
	v_pk_mul_f32 v[24:25], v[24:25], v[118:119]
	v_pk_mul_f32 v[22:23], v[22:23], v[102:103]
	v_pk_mul_f32 v[20:21], v[20:21], v[108:109]
	v_pk_mul_f32 v[18:19], v[18:19], v[110:111]
	v_pk_mul_f32 v[16:17], v[16:17], v[118:119]
	v_pk_mul_f32 v[14:15], v[14:15], v[102:103]
	v_pk_mul_f32 v[12:13], v[12:13], v[108:109]
	v_pk_mul_f32 v[10:11], v[10:11], v[110:111]
	v_pk_mul_f32 v[8:9], v[8:9], v[118:119]
	v_pk_mul_f32 v[6:7], v[6:7], v[102:103]
	v_pk_mul_f32 v[4:5], v[4:5], v[108:109]
	v_pk_mul_f32 v[2:3], v[2:3], v[110:111]
	v_pk_mul_f32 v[0:1], v[0:1], v[118:119]
	s_waitcnt vmcnt(7)
	v_lshlrev_b32_e32 v48, 16, v210
	v_and_b32_e32 v49, 0xffff0000, v210
	v_lshlrev_b32_e32 v50, 16, v211
	v_and_b32_e32 v51, 0xffff0000, v211
	v_lshlrev_b32_e32 v56, 16, v212
	v_and_b32_e32 v57, 0xffff0000, v212
	v_lshlrev_b32_e32 v58, 16, v213
	v_and_b32_e32 v59, 0xffff0000, v213
	s_waitcnt vmcnt(7)
	v_pk_add_f32 v[48:49], v[48:49], v[238:239] op_sel_hi:[1,0] neg_lo:[0,1] neg_hi:[0,1]
	v_pk_add_f32 v[50:51], v[50:51], v[238:239] op_sel_hi:[1,0] neg_lo:[0,1] neg_hi:[0,1]
	v_pk_add_f32 v[56:57], v[56:57], v[238:239] op_sel_hi:[1,0] neg_lo:[0,1] neg_hi:[0,1]
	v_pk_add_f32 v[58:59], v[58:59], v[238:239] op_sel_hi:[1,0] neg_lo:[0,1] neg_hi:[0,1]
	v_pk_mul_f32 v[48:49], v[238:239], v[48:49] op_sel:[1,0]
	v_pk_mul_f32 v[50:51], v[238:239], v[50:51] op_sel:[1,0]
	v_pk_mul_f32 v[56:57], v[238:239], v[56:57] op_sel:[1,0]
	v_pk_mul_f32 v[58:59], v[238:239], v[58:59] op_sel:[1,0]
	v_pk_fma_f32 v[48:49], v[72:73], v[48:49], v[68:69]
	v_pk_fma_f32 v[50:51], v[74:75], v[50:51], v[70:71]
	v_pk_fma_f32 v[56:57], v[64:65], v[56:57], v[76:77]
	v_pk_fma_f32 v[58:59], v[66:67], v[58:59], v[78:79]
	v_pk_fma_f32 v[52:53], v[48:49], s[22:23], v[52:53] op_sel_hi:[1,0,1]
	v_pk_fma_f32 v[54:55], v[50:51], s[22:23], v[54:55] op_sel_hi:[1,0,1]
	v_pk_fma_f32 v[56:57], v[56:57], s[22:23], v[126:127] op_sel_hi:[1,0,1]
	v_pk_fma_f32 v[58:59], v[58:59], s[22:23], v[62:63] op_sel_hi:[1,0,1]
	v_cvt_pk_bf16_f32 v52, v52, v53
	v_cvt_pk_bf16_f32 v53, v54, v55
	v_cvt_pk_bf16_f32 v54, v56, v57
	v_cvt_pk_bf16_f32 v55, v58, v59
	v_pk_mul_f32 v[56:57], v[40:41], v[118:119]
	global_store_dwordx4 v[122:123], v[52:55], off offset:256
	s_waitcnt vmcnt(7)
	v_lshlrev_b32_e32 v40, 16, v214
	v_pk_mul_f32 v[54:55], v[42:43], v[110:111]
	v_and_b32_e32 v41, 0xffff0000, v214
	v_lshlrev_b32_e32 v42, 16, v215
	v_and_b32_e32 v43, 0xffff0000, v215
	v_lshlrev_b32_e32 v48, 16, v216
	v_and_b32_e32 v49, 0xffff0000, v216
	v_lshlrev_b32_e32 v50, 16, v217
	v_and_b32_e32 v51, 0xffff0000, v217
	s_waitcnt vmcnt(7)
	v_pk_add_f32 v[40:41], v[40:41], v[240:241] op_sel_hi:[1,0] neg_lo:[0,1] neg_hi:[0,1]
	v_pk_add_f32 v[42:43], v[42:43], v[240:241] op_sel_hi:[1,0] neg_lo:[0,1] neg_hi:[0,1]
	v_pk_add_f32 v[48:49], v[48:49], v[240:241] op_sel_hi:[1,0] neg_lo:[0,1] neg_hi:[0,1]
	v_pk_add_f32 v[50:51], v[50:51], v[240:241] op_sel_hi:[1,0] neg_lo:[0,1] neg_hi:[0,1]
	v_pk_mul_f32 v[40:41], v[240:241], v[40:41] op_sel:[1,0]
	v_pk_mul_f32 v[42:43], v[240:241], v[42:43] op_sel:[1,0]
	v_pk_mul_f32 v[48:49], v[240:241], v[48:49] op_sel:[1,0]
	v_pk_mul_f32 v[50:51], v[240:241], v[50:51] op_sel:[1,0]
	v_pk_fma_f32 v[40:41], v[72:73], v[40:41], v[68:69]
	v_pk_fma_f32 v[42:43], v[74:75], v[42:43], v[70:71]
	v_pk_fma_f32 v[48:49], v[64:65], v[48:49], v[76:77]
	v_pk_fma_f32 v[50:51], v[66:67], v[50:51], v[78:79]
	v_pk_fma_f32 v[44:45], v[40:41], s[22:23], v[44:45] op_sel_hi:[1,0,1]
	v_pk_fma_f32 v[46:47], v[42:43], s[22:23], v[46:47] op_sel_hi:[1,0,1]
	v_pk_fma_f32 v[48:49], v[48:49], s[22:23], v[56:57] op_sel_hi:[1,0,1]
	v_pk_fma_f32 v[50:51], v[50:51], s[22:23], v[54:55] op_sel_hi:[1,0,1]
	v_cvt_pk_bf16_f32 v44, v44, v45
	v_cvt_pk_bf16_f32 v45, v46, v47
	v_cvt_pk_bf16_f32 v46, v48, v49
	v_cvt_pk_bf16_f32 v47, v50, v51
	s_nop 0
	global_store_dwordx4 v[114:115], v[44:47], off offset:256
	s_waitcnt vmcnt(7)
	v_lshlrev_b32_e32 v48, 16, v220
	v_lshlrev_b32_e32 v46, 16, v218
	v_and_b32_e32 v47, 0xffff0000, v218
	v_lshlrev_b32_e32 v40, 16, v219
	v_and_b32_e32 v41, 0xffff0000, v219
	v_and_b32_e32 v49, 0xffff0000, v220
	v_lshlrev_b32_e32 v42, 16, v221
	v_and_b32_e32 v43, 0xffff0000, v221
	s_waitcnt vmcnt(7)
	v_pk_add_f32 v[46:47], v[46:47], v[242:243] op_sel_hi:[1,0] neg_lo:[0,1] neg_hi:[0,1]
	v_pk_add_f32 v[40:41], v[40:41], v[242:243] op_sel_hi:[1,0] neg_lo:[0,1] neg_hi:[0,1]
	v_pk_add_f32 v[48:49], v[48:49], v[242:243] op_sel_hi:[1,0] neg_lo:[0,1] neg_hi:[0,1]
	v_pk_add_f32 v[42:43], v[42:43], v[242:243] op_sel_hi:[1,0] neg_lo:[0,1] neg_hi:[0,1]
	v_pk_mul_f32 v[46:47], v[242:243], v[46:47] op_sel:[1,0]
	v_pk_mul_f32 v[40:41], v[242:243], v[40:41] op_sel:[1,0]
	v_pk_mul_f32 v[48:49], v[242:243], v[48:49] op_sel:[1,0]
	v_pk_mul_f32 v[42:43], v[242:243], v[42:43] op_sel:[1,0]
	v_pk_fma_f32 v[44:45], v[72:73], v[46:47], v[68:69]
	v_pk_fma_f32 v[40:41], v[74:75], v[40:41], v[70:71]
	v_pk_fma_f32 v[46:47], v[64:65], v[48:49], v[76:77]
	v_pk_fma_f32 v[42:43], v[66:67], v[42:43], v[78:79]
	v_pk_fma_f32 v[36:37], v[44:45], s[22:23], v[36:37] op_sel_hi:[1,0,1]
	v_pk_fma_f32 v[38:39], v[40:41], s[22:23], v[38:39] op_sel_hi:[1,0,1]
	v_pk_fma_f32 v[40:41], v[46:47], s[22:23], v[32:33] op_sel_hi:[1,0,1]
	v_pk_fma_f32 v[42:43], v[42:43], s[22:23], v[34:35] op_sel_hi:[1,0,1]
	v_cvt_pk_bf16_f32 v32, v36, v37
	v_cvt_pk_bf16_f32 v33, v38, v39
	v_cvt_pk_bf16_f32 v34, v40, v41
	v_cvt_pk_bf16_f32 v35, v42, v43
	global_store_dwordx4 v[106:107], v[32:35], off offset:256
	s_nop 0
	s_waitcnt vmcnt(7)
	v_lshlrev_b32_e32 v38, 16, v222
	v_and_b32_e32 v39, 0xffff0000, v222
	v_lshlrev_b32_e32 v32, 16, v223
	v_and_b32_e32 v33, 0xffff0000, v223
	v_lshlrev_b32_e32 v40, 16, v224
	v_and_b32_e32 v41, 0xffff0000, v224
	v_lshlrev_b32_e32 v34, 16, v225
	v_and_b32_e32 v35, 0xffff0000, v225
	s_waitcnt vmcnt(7)
	v_pk_add_f32 v[38:39], v[38:39], v[244:245] op_sel_hi:[1,0] neg_lo:[0,1] neg_hi:[0,1]
	v_pk_add_f32 v[32:33], v[32:33], v[244:245] op_sel_hi:[1,0] neg_lo:[0,1] neg_hi:[0,1]
	v_pk_add_f32 v[40:41], v[40:41], v[244:245] op_sel_hi:[1,0] neg_lo:[0,1] neg_hi:[0,1]
	v_pk_add_f32 v[34:35], v[34:35], v[244:245] op_sel_hi:[1,0] neg_lo:[0,1] neg_hi:[0,1]
	v_pk_mul_f32 v[38:39], v[244:245], v[38:39] op_sel:[1,0]
	v_pk_mul_f32 v[32:33], v[244:245], v[32:33] op_sel:[1,0]
	v_pk_mul_f32 v[40:41], v[244:245], v[40:41] op_sel:[1,0]
	v_pk_mul_f32 v[34:35], v[244:245], v[34:35] op_sel:[1,0]
	v_pk_fma_f32 v[36:37], v[72:73], v[38:39], v[68:69]
	v_pk_fma_f32 v[32:33], v[74:75], v[32:33], v[70:71]
	v_pk_fma_f32 v[38:39], v[64:65], v[40:41], v[76:77]
	v_pk_fma_f32 v[34:35], v[66:67], v[34:35], v[78:79]
	v_pk_fma_f32 v[28:29], v[36:37], s[22:23], v[28:29] op_sel_hi:[1,0,1]
	v_pk_fma_f32 v[30:31], v[32:33], s[22:23], v[30:31] op_sel_hi:[1,0,1]
	v_pk_fma_f32 v[32:33], v[38:39], s[22:23], v[24:25] op_sel_hi:[1,0,1]
	v_pk_fma_f32 v[34:35], v[34:35], s[22:23], v[26:27] op_sel_hi:[1,0,1]
	v_cvt_pk_bf16_f32 v24, v28, v29
	v_cvt_pk_bf16_f32 v25, v30, v31
	v_cvt_pk_bf16_f32 v26, v32, v33
	v_cvt_pk_bf16_f32 v27, v34, v35
	global_store_dwordx4 v[98:99], v[24:27], off offset:256
	s_nop 0
	s_waitcnt vmcnt(7)
	v_lshlrev_b32_e32 v30, 16, v226
	v_and_b32_e32 v31, 0xffff0000, v226
	v_lshlrev_b32_e32 v24, 16, v227
	v_and_b32_e32 v25, 0xffff0000, v227
	v_lshlrev_b32_e32 v32, 16, v228
	v_and_b32_e32 v33, 0xffff0000, v228
	v_lshlrev_b32_e32 v26, 16, v229
	v_and_b32_e32 v27, 0xffff0000, v229
	s_waitcnt vmcnt(7)
	v_pk_add_f32 v[30:31], v[30:31], v[246:247] op_sel_hi:[1,0] neg_lo:[0,1] neg_hi:[0,1]
	v_pk_add_f32 v[24:25], v[24:25], v[246:247] op_sel_hi:[1,0] neg_lo:[0,1] neg_hi:[0,1]
	v_pk_add_f32 v[32:33], v[32:33], v[246:247] op_sel_hi:[1,0] neg_lo:[0,1] neg_hi:[0,1]
	v_pk_add_f32 v[26:27], v[26:27], v[246:247] op_sel_hi:[1,0] neg_lo:[0,1] neg_hi:[0,1]
	v_pk_mul_f32 v[30:31], v[246:247], v[30:31] op_sel:[1,0]
	v_pk_mul_f32 v[24:25], v[246:247], v[24:25] op_sel:[1,0]
	v_pk_mul_f32 v[32:33], v[246:247], v[32:33] op_sel:[1,0]
	v_pk_mul_f32 v[26:27], v[246:247], v[26:27] op_sel:[1,0]
	v_pk_fma_f32 v[28:29], v[72:73], v[30:31], v[68:69]
	v_pk_fma_f32 v[24:25], v[74:75], v[24:25], v[70:71]
	v_pk_fma_f32 v[30:31], v[64:65], v[32:33], v[76:77]
	v_pk_fma_f32 v[26:27], v[66:67], v[26:27], v[78:79]
	v_pk_fma_f32 v[20:21], v[28:29], s[22:23], v[20:21] op_sel_hi:[1,0,1]
	v_pk_fma_f32 v[22:23], v[24:25], s[22:23], v[22:23] op_sel_hi:[1,0,1]
	v_pk_fma_f32 v[24:25], v[30:31], s[22:23], v[16:17] op_sel_hi:[1,0,1]
	v_pk_fma_f32 v[26:27], v[26:27], s[22:23], v[18:19] op_sel_hi:[1,0,1]
	v_cvt_pk_bf16_f32 v16, v20, v21
	v_cvt_pk_bf16_f32 v17, v22, v23
	v_cvt_pk_bf16_f32 v18, v24, v25
	v_cvt_pk_bf16_f32 v19, v26, v27
	global_store_dwordx4 v[90:91], v[16:19], off offset:256
	s_nop 0
	s_waitcnt vmcnt(7)
	v_lshlrev_b32_e32 v22, 16, v230
	v_and_b32_e32 v23, 0xffff0000, v230
	v_lshlrev_b32_e32 v16, 16, v231
	v_and_b32_e32 v17, 0xffff0000, v231
	v_lshlrev_b32_e32 v24, 16, v232
	v_and_b32_e32 v25, 0xffff0000, v232
	v_lshlrev_b32_e32 v18, 16, v233
	v_and_b32_e32 v19, 0xffff0000, v233
	s_waitcnt vmcnt(7)
	v_pk_add_f32 v[22:23], v[22:23], v[250:251] op_sel_hi:[1,0] neg_lo:[0,1] neg_hi:[0,1]
	v_pk_add_f32 v[16:17], v[16:17], v[250:251] op_sel_hi:[1,0] neg_lo:[0,1] neg_hi:[0,1]
	v_pk_add_f32 v[24:25], v[24:25], v[250:251] op_sel_hi:[1,0] neg_lo:[0,1] neg_hi:[0,1]
	v_pk_add_f32 v[18:19], v[18:19], v[250:251] op_sel_hi:[1,0] neg_lo:[0,1] neg_hi:[0,1]
	v_pk_mul_f32 v[22:23], v[250:251], v[22:23] op_sel:[1,0]
	v_pk_mul_f32 v[16:17], v[250:251], v[16:17] op_sel:[1,0]
	v_pk_mul_f32 v[24:25], v[250:251], v[24:25] op_sel:[1,0]
	v_pk_mul_f32 v[18:19], v[250:251], v[18:19] op_sel:[1,0]
	v_pk_fma_f32 v[20:21], v[72:73], v[22:23], v[68:69]
	v_pk_fma_f32 v[16:17], v[74:75], v[16:17], v[70:71]
	v_pk_fma_f32 v[22:23], v[64:65], v[24:25], v[76:77]
	v_pk_fma_f32 v[18:19], v[66:67], v[18:19], v[78:79]
	v_pk_fma_f32 v[12:13], v[20:21], s[22:23], v[12:13] op_sel_hi:[1,0,1]
	v_pk_fma_f32 v[14:15], v[16:17], s[22:23], v[14:15] op_sel_hi:[1,0,1]
	v_pk_fma_f32 v[16:17], v[22:23], s[22:23], v[8:9] op_sel_hi:[1,0,1]
	v_pk_fma_f32 v[18:19], v[18:19], s[22:23], v[10:11] op_sel_hi:[1,0,1]
	v_cvt_pk_bf16_f32 v8, v12, v13
	v_cvt_pk_bf16_f32 v9, v14, v15
	v_cvt_pk_bf16_f32 v10, v16, v17
	v_cvt_pk_bf16_f32 v11, v18, v19
	global_store_dwordx4 v[84:85], v[8:11], off offset:256
	s_nop 0
	s_waitcnt vmcnt(7)
	v_lshlrev_b32_e32 v14, 16, v234
	v_and_b32_e32 v15, 0xffff0000, v234
	v_lshlrev_b32_e32 v8, 16, v235
	v_and_b32_e32 v9, 0xffff0000, v235
	v_lshlrev_b32_e32 v16, 16, v236
	v_and_b32_e32 v17, 0xffff0000, v236
	v_lshlrev_b32_e32 v10, 16, v237
	v_and_b32_e32 v11, 0xffff0000, v237
	s_waitcnt vmcnt(7)
	v_pk_add_f32 v[14:15], v[14:15], v[252:253] op_sel_hi:[1,0] neg_lo:[0,1] neg_hi:[0,1]
	v_pk_add_f32 v[8:9], v[8:9], v[252:253] op_sel_hi:[1,0] neg_lo:[0,1] neg_hi:[0,1]
	v_pk_add_f32 v[16:17], v[16:17], v[252:253] op_sel_hi:[1,0] neg_lo:[0,1] neg_hi:[0,1]
	v_pk_add_f32 v[10:11], v[10:11], v[252:253] op_sel_hi:[1,0] neg_lo:[0,1] neg_hi:[0,1]
	v_pk_mul_f32 v[14:15], v[252:253], v[14:15] op_sel:[1,0]
	v_pk_mul_f32 v[8:9], v[252:253], v[8:9] op_sel:[1,0]
	v_pk_mul_f32 v[16:17], v[252:253], v[16:17] op_sel:[1,0]
	v_pk_mul_f32 v[10:11], v[252:253], v[10:11] op_sel:[1,0]
	v_pk_fma_f32 v[12:13], v[72:73], v[14:15], v[68:69]
	v_pk_fma_f32 v[8:9], v[74:75], v[8:9], v[70:71]
	v_pk_fma_f32 v[14:15], v[64:65], v[16:17], v[76:77]
	v_pk_fma_f32 v[10:11], v[66:67], v[10:11], v[78:79]
	v_pk_fma_f32 v[4:5], v[12:13], s[22:23], v[4:5] op_sel_hi:[1,0,1]
	v_pk_fma_f32 v[6:7], v[8:9], s[22:23], v[6:7] op_sel_hi:[1,0,1]
	v_pk_fma_f32 v[8:9], v[14:15], s[22:23], v[0:1] op_sel_hi:[1,0,1]
	v_pk_fma_f32 v[10:11], v[10:11], s[22:23], v[2:3] op_sel_hi:[1,0,1]
	v_cvt_pk_bf16_f32 v0, v4, v5
	v_cvt_pk_bf16_f32 v1, v6, v7
	v_cvt_pk_bf16_f32 v2, v8, v9
	v_cvt_pk_bf16_f32 v3, v10, v11
	global_store_dwordx4 v[80:81], v[0:3], off offset:256
	s_cbranch_vccnz .LBB0_2414
	s_andn2_b64 vcc, exec, s[6:7]
	s_cbranch_vccnz .LBB0_2413
	s_barrier
	s_branch .LBB0_2413

.LBB0_2624:
	s_cmp_gt_i32 s33, 31
	v_lshl_add_u32 v182, s33, 8, v145
	v_lshl_or_b32 v166, s63, 8, v149
	s_cselect_b32 s34, 0xc000, 0
	v_ashrrev_i32_e32 v183, 31, v182
	s_add_u32 s34, s53, s34
	v_ashrrev_i32_e32 v167, 31, v166
	v_lshlrev_b64 v[168:169], 12, v[182:183]
	s_addc_u32 s35, s54, 0
	v_lshlrev_b64 v[128:129], 2, v[166:167]
	v_lshl_add_u64 v[130:131], s[10:11], 0, v[168:169]
	v_lshlrev_b64 v[180:181], 1, v[166:167]
	v_lshl_add_u64 v[172:173], s[34:35], 0, v[128:129]
	v_lshl_add_u64 v[176:177], v[130:131], 0, v[180:181]
	global_load_dwordx4 v[196:199], v[172:173], off offset:16
	global_load_dwordx4 v[186:189], v[172:173], off
	global_load_dwordx4 v[200:203], v[176:177], off
	v_lshl_add_u64 v[178:179], v[182:183], 3, s[12:13]
	global_load_dwordx2 v[204:205], v[178:179], off
	v_lshl_add_u64 v[130:131], s[14:15], 0, v[128:129]
	v_lshl_add_u64 v[140:141], s[16:17], 0, v[128:129]
	global_load_dwordx4 v[132:135], v[140:141], off
	global_load_dwordx4 v[136:139], v[130:131], off
	s_nop 0
	global_load_dwordx4 v[128:131], v[130:131], off offset:16
	s_nop 0
	global_load_dwordx4 v[140:143], v[140:141], off offset:16
	s_mov_b32 s86, 0x10000
	s_mov_b32 s87, 0
	s_mov_b32 s88, 0x50000
	s_mov_b32 s89, 0
	v_lshl_add_u64 v[208:209], v[176:177], 0, s[86:87]
	global_load_dwordx4 v[210:213], v[208:209], off
	v_lshl_add_u64 v[208:209], v[208:209], 0, s[86:87]
	global_load_dwordx4 v[214:217], v[208:209], off
	v_lshl_add_u64 v[208:209], v[208:209], 0, s[86:87]
	global_load_dwordx4 v[218:221], v[208:209], off
	v_lshl_add_u64 v[208:209], v[208:209], 0, s[88:89]
	global_load_dwordx4 v[222:225], v[208:209], off
	v_lshl_add_u64 v[208:209], v[208:209], 0, s[86:87]
	global_load_dwordx4 v[226:229], v[208:209], off
	v_lshl_add_u64 v[208:209], v[208:209], 0, s[86:87]
	global_load_dwordx4 v[230:233], v[208:209], off
	v_lshl_add_u64 v[208:209], v[208:209], 0, s[86:87]
	global_load_dwordx4 v[234:237], v[208:209], off
	global_load_dwordx2 v[238:239], v[178:179], off offset:128
	global_load_dwordx2 v[240:241], v[178:179], off offset:256
	global_load_dwordx2 v[242:243], v[178:179], off offset:384
	global_load_dwordx2 v[244:245], v[178:179], off offset:1024
	global_load_dwordx2 v[246:247], v[178:179], off offset:1152
	global_load_dwordx2 v[250:251], v[178:179], off offset:1280
	global_load_dwordx2 v[252:253], v[178:179], off offset:1408
	v_or_b32_e32 v170, 16, v182
	v_ashrrev_i32_e32 v171, 31, v170
	v_lshl_add_u64 v[174:175], s[18:19], 0, v[168:169]
	v_lshlrev_b64 v[206:207], 12, v[170:171]
	v_lshl_add_u64 v[168:169], v[170:171], 3, s[12:13]
	v_lshl_add_u64 v[170:171], v[174:175], 0, v[180:181]
	v_lshl_add_u64 v[174:175], s[10:11], 0, v[206:207]
	v_lshl_add_u64 v[174:175], v[174:175], 0, v[180:181]
	s_and_b64 vcc, exec, s[0:1]
	s_mov_b64 s[0:1], -1
	s_waitcnt vmcnt(14)
	v_pk_add_f32 v[190:191], v[196:197], 1.0 op_sel_hi:[1,0]
	v_pk_add_f32 v[184:185], v[188:189], 1.0 op_sel_hi:[1,0]
	v_pk_add_f32 v[188:189], v[198:199], 1.0 op_sel_hi:[1,0]
	v_lshlrev_b32_e32 v196, 16, v200
	v_and_b32_e32 v197, 0xffff0000, v200
	v_lshlrev_b32_e32 v198, 16, v201
	v_and_b32_e32 v199, 0xffff0000, v201
	v_lshlrev_b32_e32 v200, 16, v202
	v_and_b32_e32 v201, 0xffff0000, v202
	v_lshlrev_b32_e32 v202, 16, v203
	v_and_b32_e32 v203, 0xffff0000, v203
	v_pk_add_f32 v[196:197], v[196:197], v[204:205] op_sel_hi:[1,0] neg_lo:[0,1] neg_hi:[0,1]
	v_pk_add_f32 v[198:199], v[198:199], v[204:205] op_sel_hi:[1,0] neg_lo:[0,1] neg_hi:[0,1]
	v_pk_add_f32 v[200:201], v[200:201], v[204:205] op_sel_hi:[1,0] neg_lo:[0,1] neg_hi:[0,1]
	v_pk_add_f32 v[202:203], v[202:203], v[204:205] op_sel_hi:[1,0] neg_lo:[0,1] neg_hi:[0,1]
	v_pk_add_f32 v[186:187], v[186:187], 1.0 op_sel_hi:[1,0]
	v_pk_mul_f32 v[196:197], v[204:205], v[196:197] op_sel:[1,0]
	v_pk_mul_f32 v[198:199], v[204:205], v[198:199] op_sel:[1,0]
	v_pk_mul_f32 v[200:201], v[204:205], v[200:201] op_sel:[1,0]
	v_pk_mul_f32 v[202:203], v[204:205], v[202:203] op_sel:[1,0]
	v_pk_mul_f32 v[126:127], v[126:127], v[184:185]
	v_pk_mul_f32 v[124:125], v[124:125], v[186:187]
	v_pk_mul_f32 v[122:123], v[122:123], v[188:189]
	v_pk_mul_f32 v[120:121], v[120:121], v[190:191]
	v_pk_fma_f32 v[196:197], v[136:137], v[196:197], v[132:133]
	v_pk_fma_f32 v[198:199], v[138:139], v[198:199], v[134:135]
	v_pk_fma_f32 v[200:201], v[128:129], v[200:201], v[140:141]
	v_pk_fma_f32 v[202:203], v[130:131], v[202:203], v[142:143]
	v_pk_fma_f32 v[124:125], v[196:197], s[24:25], v[124:125] op_sel_hi:[1,0,1]
	v_pk_fma_f32 v[126:127], v[198:199], s[24:25], v[126:127] op_sel_hi:[1,0,1]
	v_pk_fma_f32 v[200:201], v[200:201], s[24:25], v[120:121] op_sel_hi:[1,0,1]
	v_pk_fma_f32 v[202:203], v[202:203], s[24:25], v[122:123] op_sel_hi:[1,0,1]
	v_cvt_pk_bf16_f32 v120, v124, v125
	v_cvt_pk_bf16_f32 v121, v126, v127
	v_cvt_pk_bf16_f32 v122, v200, v201
	v_cvt_pk_bf16_f32 v123, v202, v203
	v_pk_mul_f32 v[118:119], v[118:119], v[184:185]
	global_store_dwordx4 v[170:171], v[120:123], off
	v_pk_mul_f32 v[116:117], v[116:117], v[186:187]
	s_nop 1
	v_or_b32_e32 v122, 32, v182
	v_ashrrev_i32_e32 v123, 31, v122
	v_lshlrev_b64 v[200:201], 12, v[122:123]
	v_pk_mul_f32 v[114:115], v[114:115], v[188:189]
	v_pk_mul_f32 v[112:113], v[112:113], v[190:191]
	v_lshl_add_u64 v[120:121], v[122:123], 3, s[12:13]
	v_lshl_add_u64 v[122:123], s[18:19], 0, v[206:207]
	v_lshl_add_u64 v[124:125], s[10:11], 0, v[200:201]
	v_lshl_add_u64 v[122:123], v[122:123], 0, v[180:181]
	v_lshl_add_u64 v[124:125], v[124:125], 0, v[180:181]
	v_pk_mul_f32 v[110:111], v[110:111], v[184:185]
	v_pk_mul_f32 v[108:109], v[108:109], v[186:187]
	v_pk_mul_f32 v[106:107], v[106:107], v[188:189]
	v_pk_mul_f32 v[104:105], v[104:105], v[190:191]
	v_pk_mul_f32 v[102:103], v[102:103], v[184:185]
	v_pk_mul_f32 v[100:101], v[100:101], v[186:187]
	v_pk_mul_f32 v[98:99], v[98:99], v[188:189]
	v_pk_mul_f32 v[96:97], v[96:97], v[190:191]
	v_pk_mul_f32 v[94:95], v[94:95], v[184:185]
	v_pk_mul_f32 v[92:93], v[92:93], v[186:187]
	v_pk_mul_f32 v[90:91], v[90:91], v[188:189]
	v_pk_mul_f32 v[88:89], v[88:89], v[190:191]
	v_pk_mul_f32 v[86:87], v[86:87], v[184:185]
	v_pk_mul_f32 v[84:85], v[84:85], v[186:187]
	v_pk_mul_f32 v[82:83], v[82:83], v[188:189]
	v_pk_mul_f32 v[80:81], v[80:81], v[190:191]
	v_pk_mul_f32 v[78:79], v[78:79], v[184:185]
	v_pk_mul_f32 v[76:77], v[76:77], v[186:187]
	v_pk_mul_f32 v[74:75], v[74:75], v[188:189]
	v_pk_mul_f32 v[72:73], v[72:73], v[190:191]
	v_pk_mul_f32 v[70:71], v[70:71], v[184:185]
	v_pk_mul_f32 v[68:69], v[68:69], v[186:187]
	v_pk_mul_f32 v[66:67], v[66:67], v[188:189]
	v_pk_mul_f32 v[64:65], v[64:65], v[190:191]
	s_waitcnt vmcnt(14)
	v_lshlrev_b32_e32 v202, 16, v210
	v_and_b32_e32 v203, 0xffff0000, v210
	v_lshlrev_b32_e32 v196, 16, v211
	v_and_b32_e32 v197, 0xffff0000, v211
	v_lshlrev_b32_e32 v204, 16, v212
	v_and_b32_e32 v205, 0xffff0000, v212
	v_lshlrev_b32_e32 v198, 16, v213
	v_and_b32_e32 v199, 0xffff0000, v213
	s_waitcnt vmcnt(7)
	v_pk_add_f32 v[202:203], v[202:203], v[238:239] op_sel_hi:[1,0] neg_lo:[0,1] neg_hi:[0,1]
	v_pk_add_f32 v[196:197], v[196:197], v[238:239] op_sel_hi:[1,0] neg_lo:[0,1] neg_hi:[0,1]
	v_pk_add_f32 v[204:205], v[204:205], v[238:239] op_sel_hi:[1,0] neg_lo:[0,1] neg_hi:[0,1]
	v_pk_add_f32 v[198:199], v[198:199], v[238:239] op_sel_hi:[1,0] neg_lo:[0,1] neg_hi:[0,1]
	v_pk_mul_f32 v[202:203], v[238:239], v[202:203] op_sel:[1,0]
	v_pk_mul_f32 v[196:197], v[238:239], v[196:197] op_sel:[1,0]
	v_pk_mul_f32 v[204:205], v[238:239], v[204:205] op_sel:[1,0]
	v_pk_mul_f32 v[126:127], v[238:239], v[198:199] op_sel:[1,0]
	v_pk_fma_f32 v[198:199], v[136:137], v[202:203], v[132:133]
	v_pk_fma_f32 v[196:197], v[138:139], v[196:197], v[134:135]
	v_pk_fma_f32 v[202:203], v[128:129], v[204:205], v[140:141]
	v_pk_fma_f32 v[126:127], v[130:131], v[126:127], v[142:143]
	v_pk_fma_f32 v[116:117], v[198:199], s[24:25], v[116:117] op_sel_hi:[1,0,1]
	v_pk_fma_f32 v[118:119], v[196:197], s[24:25], v[118:119] op_sel_hi:[1,0,1]
	v_pk_fma_f32 v[202:203], v[202:203], s[24:25], v[112:113] op_sel_hi:[1,0,1]
	v_pk_fma_f32 v[126:127], v[126:127], s[24:25], v[114:115] op_sel_hi:[1,0,1]
	v_cvt_pk_bf16_f32 v112, v116, v117
	v_cvt_pk_bf16_f32 v113, v118, v119
	v_cvt_pk_bf16_f32 v114, v202, v203
	v_cvt_pk_bf16_f32 v115, v126, v127
	s_nop 0
	global_store_dwordx4 v[122:123], v[112:115], off
	s_waitcnt vmcnt(8)
	v_lshlrev_b32_e32 v202, 16, v216
	v_or_b32_e32 v114, 48, v182
	v_ashrrev_i32_e32 v115, 31, v114
	v_lshl_add_u64 v[112:113], v[114:115], 3, s[12:13]
	v_lshlrev_b64 v[126:127], 12, v[114:115]
	v_lshl_add_u64 v[114:115], s[18:19], 0, v[200:201]
	v_lshlrev_b32_e32 v200, 16, v214
	v_and_b32_e32 v201, 0xffff0000, v214
	v_lshlrev_b32_e32 v196, 16, v215
	v_and_b32_e32 v197, 0xffff0000, v215
	v_and_b32_e32 v203, 0xffff0000, v216
	v_lshlrev_b32_e32 v198, 16, v217
	v_and_b32_e32 v199, 0xffff0000, v217
	s_waitcnt vmcnt(7)
	v_pk_add_f32 v[200:201], v[200:201], v[240:241] op_sel_hi:[1,0] neg_lo:[0,1] neg_hi:[0,1]
	v_pk_add_f32 v[196:197], v[196:197], v[240:241] op_sel_hi:[1,0] neg_lo:[0,1] neg_hi:[0,1]
	v_pk_add_f32 v[202:203], v[202:203], v[240:241] op_sel_hi:[1,0] neg_lo:[0,1] neg_hi:[0,1]
	v_pk_add_f32 v[198:199], v[198:199], v[240:241] op_sel_hi:[1,0] neg_lo:[0,1] neg_hi:[0,1]
	v_pk_mul_f32 v[200:201], v[240:241], v[200:201] op_sel:[1,0]
	v_pk_mul_f32 v[196:197], v[240:241], v[196:197] op_sel:[1,0]
	v_pk_mul_f32 v[202:203], v[240:241], v[202:203] op_sel:[1,0]
	v_pk_mul_f32 v[118:119], v[240:241], v[198:199] op_sel:[1,0]
	v_pk_fma_f32 v[198:199], v[136:137], v[200:201], v[132:133]
	v_pk_fma_f32 v[196:197], v[138:139], v[196:197], v[134:135]
	v_pk_fma_f32 v[200:201], v[128:129], v[202:203], v[140:141]
	v_pk_fma_f32 v[118:119], v[130:131], v[118:119], v[142:143]
	v_lshl_add_u64 v[116:117], s[10:11], 0, v[126:127]
	v_pk_fma_f32 v[198:199], v[198:199], s[24:25], v[108:109] op_sel_hi:[1,0,1]
	v_pk_fma_f32 v[196:197], v[196:197], s[24:25], v[110:111] op_sel_hi:[1,0,1]
	v_pk_fma_f32 v[200:201], v[200:201], s[24:25], v[104:105] op_sel_hi:[1,0,1]
	v_pk_fma_f32 v[118:119], v[118:119], s[24:25], v[106:107] op_sel_hi:[1,0,1]
	v_lshl_add_u64 v[114:115], v[114:115], 0, v[180:181]
	v_lshl_add_u64 v[116:117], v[116:117], 0, v[180:181]
	v_cvt_pk_bf16_f32 v104, v198, v199
	v_cvt_pk_bf16_f32 v105, v196, v197
	v_cvt_pk_bf16_f32 v106, v200, v201
	v_cvt_pk_bf16_f32 v107, v118, v119
	v_add_u32_e32 v196, 0x80, v182
	global_store_dwordx4 v[114:115], v[104:107], off
	v_ashrrev_i32_e32 v197, 31, v196
	v_lshlrev_b64 v[198:199], 12, v[196:197]
	v_lshl_add_u64 v[104:105], s[18:19], 0, v[126:127]
	v_lshl_add_u64 v[126:127], s[10:11], 0, v[198:199]
	v_lshl_add_u64 v[106:107], v[104:105], 0, v[180:181]
	v_lshl_add_u64 v[104:105], v[126:127], 0, v[180:181]
	s_waitcnt vmcnt(8)
	v_lshlrev_b32_e32 v126, 16, v218
	v_and_b32_e32 v127, 0xffff0000, v218
	v_lshlrev_b32_e32 v108, 16, v219
	v_and_b32_e32 v109, 0xffff0000, v219
	v_lshlrev_b32_e32 v200, 16, v220
	v_and_b32_e32 v201, 0xffff0000, v220
	v_lshlrev_b32_e32 v110, 16, v221
	v_and_b32_e32 v111, 0xffff0000, v221
	s_waitcnt vmcnt(7)
	v_pk_add_f32 v[126:127], v[126:127], v[242:243] op_sel_hi:[1,0] neg_lo:[0,1] neg_hi:[0,1]
	v_pk_add_f32 v[108:109], v[108:109], v[242:243] op_sel_hi:[1,0] neg_lo:[0,1] neg_hi:[0,1]
	v_pk_add_f32 v[200:201], v[200:201], v[242:243] op_sel_hi:[1,0] neg_lo:[0,1] neg_hi:[0,1]
	v_pk_add_f32 v[110:111], v[110:111], v[242:243] op_sel_hi:[1,0] neg_lo:[0,1] neg_hi:[0,1]
	v_pk_mul_f32 v[126:127], v[242:243], v[126:127] op_sel:[1,0]
	v_pk_mul_f32 v[108:109], v[242:243], v[108:109] op_sel:[1,0]
	v_pk_mul_f32 v[200:201], v[242:243], v[200:201] op_sel:[1,0]
	v_pk_mul_f32 v[110:111], v[242:243], v[110:111] op_sel:[1,0]
	v_pk_fma_f32 v[118:119], v[136:137], v[126:127], v[132:133]
	v_pk_fma_f32 v[108:109], v[138:139], v[108:109], v[134:135]
	v_pk_fma_f32 v[126:127], v[128:129], v[200:201], v[140:141]
	v_pk_fma_f32 v[110:111], v[130:131], v[110:111], v[142:143]
	v_pk_fma_f32 v[100:101], v[118:119], s[24:25], v[100:101] op_sel_hi:[1,0,1]
	v_pk_fma_f32 v[102:103], v[108:109], s[24:25], v[102:103] op_sel_hi:[1,0,1]
	v_pk_fma_f32 v[108:109], v[126:127], s[24:25], v[96:97] op_sel_hi:[1,0,1]
	v_pk_fma_f32 v[110:111], v[110:111], s[24:25], v[98:99] op_sel_hi:[1,0,1]
	v_cvt_pk_bf16_f32 v96, v100, v101
	v_cvt_pk_bf16_f32 v97, v102, v103
	v_cvt_pk_bf16_f32 v98, v108, v109
	v_cvt_pk_bf16_f32 v99, v110, v111
	global_store_dwordx4 v[106:107], v[96:99], off
	v_lshl_add_u64 v[100:101], v[196:197], 3, s[12:13]
	v_add_u32_e32 v118, 0x90, v182
	v_ashrrev_i32_e32 v119, 31, v118
	v_lshlrev_b64 v[126:127], 12, v[118:119]
	v_lshl_add_u64 v[96:97], s[18:19], 0, v[198:199]
	v_lshl_add_u64 v[196:197], s[10:11], 0, v[126:127]
	v_lshl_add_u64 v[98:99], v[96:97], 0, v[180:181]
	v_lshl_add_u64 v[96:97], v[196:197], 0, v[180:181]
	s_waitcnt vmcnt(8)
	v_lshlrev_b32_e32 v196, 16, v222
	v_and_b32_e32 v197, 0xffff0000, v222
	v_lshlrev_b32_e32 v108, 16, v223
	v_and_b32_e32 v109, 0xffff0000, v223
	v_lshlrev_b32_e32 v198, 16, v224
	v_and_b32_e32 v199, 0xffff0000, v224
	v_lshlrev_b32_e32 v110, 16, v225
	v_and_b32_e32 v111, 0xffff0000, v225
	s_waitcnt vmcnt(7)
	v_pk_add_f32 v[196:197], v[196:197], v[244:245] op_sel_hi:[1,0] neg_lo:[0,1] neg_hi:[0,1]
	v_pk_add_f32 v[108:109], v[108:109], v[244:245] op_sel_hi:[1,0] neg_lo:[0,1] neg_hi:[0,1]
	v_pk_add_f32 v[198:199], v[198:199], v[244:245] op_sel_hi:[1,0] neg_lo:[0,1] neg_hi:[0,1]
	v_pk_add_f32 v[110:111], v[110:111], v[244:245] op_sel_hi:[1,0] neg_lo:[0,1] neg_hi:[0,1]
	v_pk_mul_f32 v[196:197], v[244:245], v[196:197] op_sel:[1,0]
	v_pk_mul_f32 v[108:109], v[244:245], v[108:109] op_sel:[1,0]
	v_pk_mul_f32 v[198:199], v[244:245], v[198:199] op_sel:[1,0]
	v_pk_mul_f32 v[102:103], v[244:245], v[110:111] op_sel:[1,0]
	v_pk_fma_f32 v[110:111], v[136:137], v[196:197], v[132:133]
	v_pk_fma_f32 v[108:109], v[138:139], v[108:109], v[134:135]
	v_pk_fma_f32 v[196:197], v[128:129], v[198:199], v[140:141]
	v_pk_fma_f32 v[102:103], v[130:131], v[102:103], v[142:143]
	v_pk_fma_f32 v[92:93], v[110:111], s[24:25], v[92:93] op_sel_hi:[1,0,1]
	v_pk_fma_f32 v[94:95], v[108:109], s[24:25], v[94:95] op_sel_hi:[1,0,1]
	v_pk_fma_f32 v[108:109], v[196:197], s[24:25], v[88:89] op_sel_hi:[1,0,1]
	v_pk_fma_f32 v[102:103], v[102:103], s[24:25], v[90:91] op_sel_hi:[1,0,1]
	v_cvt_pk_bf16_f32 v88, v92, v93
	v_cvt_pk_bf16_f32 v89, v94, v95
	v_cvt_pk_bf16_f32 v90, v108, v109
	v_cvt_pk_bf16_f32 v91, v102, v103
	global_store_dwordx4 v[98:99], v[88:91], off
	v_lshl_add_u64 v[92:93], v[118:119], 3, s[12:13]
	v_add_u32_e32 v102, 0xa0, v182
	v_ashrrev_i32_e32 v103, 31, v102
	v_lshlrev_b64 v[118:119], 12, v[102:103]
	v_lshl_add_u64 v[88:89], s[18:19], 0, v[126:127]
	v_lshl_add_u64 v[126:127], s[10:11], 0, v[118:119]
	v_lshl_add_u64 v[90:91], v[88:89], 0, v[180:181]
	v_lshl_add_u64 v[88:89], v[126:127], 0, v[180:181]
	s_waitcnt vmcnt(8)
	v_lshlrev_b32_e32 v126, 16, v226
	v_and_b32_e32 v127, 0xffff0000, v226
	v_lshlrev_b32_e32 v108, 16, v227
	v_and_b32_e32 v109, 0xffff0000, v227
	v_lshlrev_b32_e32 v196, 16, v228
	v_and_b32_e32 v197, 0xffff0000, v228
	v_lshlrev_b32_e32 v110, 16, v229
	v_and_b32_e32 v111, 0xffff0000, v229
	s_waitcnt vmcnt(7)
	v_pk_add_f32 v[126:127], v[126:127], v[246:247] op_sel_hi:[1,0] neg_lo:[0,1] neg_hi:[0,1]
	v_pk_add_f32 v[108:109], v[108:109], v[246:247] op_sel_hi:[1,0] neg_lo:[0,1] neg_hi:[0,1]
	v_pk_add_f32 v[196:197], v[196:197], v[246:247] op_sel_hi:[1,0] neg_lo:[0,1] neg_hi:[0,1]
	v_pk_add_f32 v[110:111], v[110:111], v[246:247] op_sel_hi:[1,0] neg_lo:[0,1] neg_hi:[0,1]
	v_pk_mul_f32 v[126:127], v[246:247], v[126:127] op_sel:[1,0]
	v_pk_mul_f32 v[108:109], v[246:247], v[108:109] op_sel:[1,0]
	v_pk_mul_f32 v[196:197], v[246:247], v[196:197] op_sel:[1,0]
	v_pk_mul_f32 v[94:95], v[246:247], v[110:111] op_sel:[1,0]
	v_pk_fma_f32 v[110:111], v[136:137], v[126:127], v[132:133]
	v_pk_fma_f32 v[108:109], v[138:139], v[108:109], v[134:135]
	v_pk_fma_f32 v[126:127], v[128:129], v[196:197], v[140:141]
	v_pk_fma_f32 v[94:95], v[130:131], v[94:95], v[142:143]
	v_pk_fma_f32 v[84:85], v[110:111], s[24:25], v[84:85] op_sel_hi:[1,0,1]
	v_pk_fma_f32 v[86:87], v[108:109], s[24:25], v[86:87] op_sel_hi:[1,0,1]
	v_pk_fma_f32 v[108:109], v[126:127], s[24:25], v[80:81] op_sel_hi:[1,0,1]
	v_pk_fma_f32 v[94:95], v[94:95], s[24:25], v[82:83] op_sel_hi:[1,0,1]
	v_cvt_pk_bf16_f32 v80, v84, v85
	v_cvt_pk_bf16_f32 v81, v86, v87
	v_cvt_pk_bf16_f32 v82, v108, v109
	v_cvt_pk_bf16_f32 v83, v94, v95
	global_store_dwordx4 v[90:91], v[80:83], off
	v_lshl_add_u64 v[86:87], v[102:103], 3, s[12:13]
	v_add_u32_e32 v94, 0xb0, v182
	v_ashrrev_i32_e32 v95, 31, v94
	v_lshlrev_b64 v[102:103], 12, v[94:95]
	v_lshl_add_u64 v[80:81], s[18:19], 0, v[118:119]
	v_lshl_add_u64 v[118:119], s[10:11], 0, v[102:103]
	v_lshl_add_u64 v[82:83], v[80:81], 0, v[180:181]
	v_lshl_add_u64 v[80:81], v[118:119], 0, v[180:181]
	v_lshl_add_u64 v[94:95], v[94:95], 3, s[12:13]
	s_waitcnt vmcnt(8)
	v_lshlrev_b32_e32 v118, 16, v230
	v_and_b32_e32 v119, 0xffff0000, v230
	v_lshlrev_b32_e32 v108, 16, v231
	v_and_b32_e32 v109, 0xffff0000, v231
	v_lshlrev_b32_e32 v126, 16, v232
	v_and_b32_e32 v127, 0xffff0000, v232
	v_lshlrev_b32_e32 v110, 16, v233
	v_and_b32_e32 v111, 0xffff0000, v233
	s_waitcnt vmcnt(7)
	v_pk_add_f32 v[118:119], v[118:119], v[250:251] op_sel_hi:[1,0] neg_lo:[0,1] neg_hi:[0,1]
	v_pk_add_f32 v[108:109], v[108:109], v[250:251] op_sel_hi:[1,0] neg_lo:[0,1] neg_hi:[0,1]
	v_pk_add_f32 v[126:127], v[126:127], v[250:251] op_sel_hi:[1,0] neg_lo:[0,1] neg_hi:[0,1]
	v_pk_add_f32 v[110:111], v[110:111], v[250:251] op_sel_hi:[1,0] neg_lo:[0,1] neg_hi:[0,1]
	v_pk_mul_f32 v[118:119], v[250:251], v[118:119] op_sel:[1,0]
	v_pk_mul_f32 v[108:109], v[250:251], v[108:109] op_sel:[1,0]
	v_pk_mul_f32 v[126:127], v[250:251], v[126:127] op_sel:[1,0]
	v_pk_mul_f32 v[84:85], v[250:251], v[110:111] op_sel:[1,0]
	v_pk_fma_f32 v[110:111], v[136:137], v[118:119], v[132:133]
	v_pk_fma_f32 v[108:109], v[138:139], v[108:109], v[134:135]
	v_pk_fma_f32 v[118:119], v[128:129], v[126:127], v[140:141]
	v_pk_fma_f32 v[84:85], v[130:131], v[84:85], v[142:143]
	v_pk_fma_f32 v[76:77], v[110:111], s[24:25], v[76:77] op_sel_hi:[1,0,1]
	v_pk_fma_f32 v[78:79], v[108:109], s[24:25], v[78:79] op_sel_hi:[1,0,1]
	v_pk_fma_f32 v[108:109], v[118:119], s[24:25], v[72:73] op_sel_hi:[1,0,1]
	v_pk_fma_f32 v[84:85], v[84:85], s[24:25], v[74:75] op_sel_hi:[1,0,1]
	v_cvt_pk_bf16_f32 v72, v76, v77
	v_cvt_pk_bf16_f32 v73, v78, v79
	v_cvt_pk_bf16_f32 v74, v108, v109
	v_cvt_pk_bf16_f32 v75, v84, v85
	global_store_dwordx4 v[82:83], v[72:75], off
	v_lshl_add_u64 v[78:79], s[18:19], 0, v[102:103]
	v_lshl_add_u64 v[84:85], v[78:79], 0, v[180:181]
	s_waitcnt vmcnt(8)
	v_lshlrev_b32_e32 v78, 16, v234
	v_and_b32_e32 v79, 0xffff0000, v234
	v_lshlrev_b32_e32 v72, 16, v235
	v_and_b32_e32 v73, 0xffff0000, v235
	v_lshlrev_b32_e32 v102, 16, v236
	v_and_b32_e32 v103, 0xffff0000, v236
	v_lshlrev_b32_e32 v74, 16, v237
	v_and_b32_e32 v75, 0xffff0000, v237
	s_waitcnt vmcnt(7)
	v_pk_add_f32 v[78:79], v[78:79], v[252:253] op_sel_hi:[1,0] neg_lo:[0,1] neg_hi:[0,1]
	v_pk_add_f32 v[72:73], v[72:73], v[252:253] op_sel_hi:[1,0] neg_lo:[0,1] neg_hi:[0,1]
	v_pk_add_f32 v[102:103], v[102:103], v[252:253] op_sel_hi:[1,0] neg_lo:[0,1] neg_hi:[0,1]
	v_pk_add_f32 v[74:75], v[74:75], v[252:253] op_sel_hi:[1,0] neg_lo:[0,1] neg_hi:[0,1]
	v_pk_mul_f32 v[78:79], v[252:253], v[78:79] op_sel:[1,0]
	v_pk_mul_f32 v[72:73], v[252:253], v[72:73] op_sel:[1,0]
	v_pk_mul_f32 v[102:103], v[252:253], v[102:103] op_sel:[1,0]
	v_pk_mul_f32 v[74:75], v[252:253], v[74:75] op_sel:[1,0]
	v_pk_fma_f32 v[76:77], v[136:137], v[78:79], v[132:133]
	v_pk_fma_f32 v[72:73], v[138:139], v[72:73], v[134:135]
	v_pk_fma_f32 v[78:79], v[128:129], v[102:103], v[140:141]
	v_pk_fma_f32 v[74:75], v[130:131], v[74:75], v[142:143]
	v_pk_fma_f32 v[68:69], v[76:77], s[24:25], v[68:69] op_sel_hi:[1,0,1]
	v_pk_fma_f32 v[70:71], v[72:73], s[24:25], v[70:71] op_sel_hi:[1,0,1]
	v_pk_fma_f32 v[72:73], v[78:79], s[24:25], v[64:65] op_sel_hi:[1,0,1]
	v_pk_fma_f32 v[74:75], v[74:75], s[24:25], v[66:67] op_sel_hi:[1,0,1]
	v_cvt_pk_bf16_f32 v64, v68, v69
	v_cvt_pk_bf16_f32 v65, v70, v71
	v_cvt_pk_bf16_f32 v66, v72, v73
	v_cvt_pk_bf16_f32 v67, v74, v75
	global_store_dwordx4 v[84:85], v[64:67], off
	global_load_dwordx4 v[108:111], v[172:173], off offset:512
	global_load_dwordx4 v[126:129], v[172:173], off offset:528
	global_load_dwordx4 v[130:133], v[176:177], off offset:256
	global_load_dwordx2 v[134:135], v[178:179], off
	v_or_b32_e32 v64, 0x80, v166
	v_ashrrev_i32_e32 v65, 31, v64
	v_lshlrev_b64 v[64:65], 2, v[64:65]
	v_lshl_add_u64 v[66:67], s[14:15], 0, v[64:65]
	v_lshl_add_u64 v[76:77], s[16:17], 0, v[64:65]
	global_load_dwordx4 v[68:71], v[76:77], off
	global_load_dwordx4 v[72:75], v[66:67], off
	s_nop 0
	global_load_dwordx4 v[64:67], v[66:67], off offset:16
	s_nop 0
	global_load_dwordx4 v[76:79], v[76:77], off offset:16
	v_lshl_add_u64 v[208:209], v[176:177], 0, s[86:87]
	global_load_dwordx4 v[210:213], v[208:209], off offset:256
	v_lshl_add_u64 v[208:209], v[208:209], 0, s[86:87]
	global_load_dwordx4 v[214:217], v[208:209], off offset:256
	v_lshl_add_u64 v[208:209], v[208:209], 0, s[86:87]
	global_load_dwordx4 v[218:221], v[208:209], off offset:256
	v_lshl_add_u64 v[208:209], v[208:209], 0, s[88:89]
	global_load_dwordx4 v[222:225], v[208:209], off offset:256
	v_lshl_add_u64 v[208:209], v[208:209], 0, s[86:87]
	global_load_dwordx4 v[226:229], v[208:209], off offset:256
	v_lshl_add_u64 v[208:209], v[208:209], 0, s[86:87]
	global_load_dwordx4 v[230:233], v[208:209], off offset:256
	v_lshl_add_u64 v[208:209], v[208:209], 0, s[86:87]
	global_load_dwordx4 v[234:237], v[208:209], off offset:256
	s_waitcnt vmcnt(14)
	v_pk_add_f32 v[102:103], v[110:111], 1.0 op_sel_hi:[1,0]
	s_waitcnt vmcnt(13)
	v_pk_add_f32 v[110:111], v[128:129], 1.0 op_sel_hi:[1,0]
	v_pk_add_f32 v[118:119], v[126:127], 1.0 op_sel_hi:[1,0]
	s_waitcnt vmcnt(12)
	v_lshlrev_b32_e32 v126, 16, v130
	v_and_b32_e32 v127, 0xffff0000, v130
	v_lshlrev_b32_e32 v128, 16, v131
	v_and_b32_e32 v129, 0xffff0000, v131
	v_lshlrev_b32_e32 v130, 16, v132
	v_and_b32_e32 v131, 0xffff0000, v132
	v_lshlrev_b32_e32 v132, 16, v133
	v_and_b32_e32 v133, 0xffff0000, v133
	s_waitcnt vmcnt(11)
	v_pk_add_f32 v[126:127], v[126:127], v[134:135] op_sel_hi:[1,0] neg_lo:[0,1] neg_hi:[0,1]
	v_pk_add_f32 v[128:129], v[128:129], v[134:135] op_sel_hi:[1,0] neg_lo:[0,1] neg_hi:[0,1]
	v_pk_add_f32 v[130:131], v[130:131], v[134:135] op_sel_hi:[1,0] neg_lo:[0,1] neg_hi:[0,1]
	v_pk_mul_f32 v[138:139], v[56:57], v[118:119]
	v_pk_add_f32 v[56:57], v[132:133], v[134:135] op_sel_hi:[1,0] neg_lo:[0,1] neg_hi:[0,1]
	v_pk_add_f32 v[108:109], v[108:109], 1.0 op_sel_hi:[1,0]
	v_pk_mul_f32 v[136:137], v[58:59], v[110:111]
	v_pk_mul_f32 v[58:59], v[134:135], v[126:127] op_sel:[1,0]
	v_pk_mul_f32 v[126:127], v[134:135], v[128:129] op_sel:[1,0]
	v_pk_mul_f32 v[128:129], v[134:135], v[130:131] op_sel:[1,0]
	v_pk_mul_f32 v[56:57], v[134:135], v[56:57] op_sel:[1,0]
	v_pk_mul_f32 v[62:63], v[62:63], v[102:103]
	v_pk_mul_f32 v[60:61], v[60:61], v[108:109]
	s_waitcnt vmcnt(9)
	v_pk_fma_f32 v[58:59], v[72:73], v[58:59], v[68:69]
	v_pk_fma_f32 v[126:127], v[74:75], v[126:127], v[70:71]
	s_waitcnt vmcnt(7)
	v_pk_fma_f32 v[128:129], v[64:65], v[128:129], v[76:77]
	v_pk_fma_f32 v[130:131], v[66:67], v[56:57], v[78:79]
	v_pk_fma_f32 v[60:61], v[58:59], s[24:25], v[60:61] op_sel_hi:[1,0,1]
	v_pk_fma_f32 v[62:63], v[126:127], s[24:25], v[62:63] op_sel_hi:[1,0,1]
	v_pk_fma_f32 v[126:127], v[128:129], s[24:25], v[138:139] op_sel_hi:[1,0,1]
	v_pk_fma_f32 v[128:129], v[130:131], s[24:25], v[136:137] op_sel_hi:[1,0,1]
	v_cvt_pk_bf16_f32 v60, v60, v61
	v_cvt_pk_bf16_f32 v61, v62, v63
	v_cvt_pk_bf16_f32 v62, v126, v127
	v_cvt_pk_bf16_f32 v63, v128, v129
	v_pk_mul_f32 v[126:127], v[48:49], v[118:119]
	global_store_dwordx4 v[170:171], v[60:63], off offset:256
	v_pk_mul_f32 v[54:55], v[54:55], v[102:103]
	s_nop 1
	v_pk_mul_f32 v[62:63], v[50:51], v[110:111]
	v_pk_mul_f32 v[52:53], v[52:53], v[108:109]
	v_pk_mul_f32 v[46:47], v[46:47], v[102:103]
	v_pk_mul_f32 v[44:45], v[44:45], v[108:109]
	v_pk_mul_f32 v[38:39], v[38:39], v[102:103]
	v_pk_mul_f32 v[36:37], v[36:37], v[108:109]
	v_pk_mul_f32 v[34:35], v[34:35], v[110:111]
	v_pk_mul_f32 v[32:33], v[32:33], v[118:119]
	v_pk_mul_f32 v[30:31], v[30:31], v[102:103]
	v_pk_mul_f32 v[28:29], v[28:29], v[108:109]
	v_pk_mul_f32 v[26:27], v[26:27], v[110:111]
	v_pk_mul_f32 v[24:25], v[24:25], v[118:119]
	v_pk_mul_f32 v[22:23], v[22:23], v[102:103]
	v_pk_mul_f32 v[20:21], v[20:21], v[108:109]
	v_pk_mul_f32 v[18:19], v[18:19], v[110:111]
	v_pk_mul_f32 v[16:17], v[16:17], v[118:119]
	v_pk_mul_f32 v[14:15], v[14:15], v[102:103]
	v_pk_mul_f32 v[12:13], v[12:13], v[108:109]
	v_pk_mul_f32 v[10:11], v[10:11], v[110:111]
	v_pk_mul_f32 v[8:9], v[8:9], v[118:119]
	v_pk_mul_f32 v[6:7], v[6:7], v[102:103]
	v_pk_mul_f32 v[4:5], v[4:5], v[108:109]
	v_pk_mul_f32 v[2:3], v[2:3], v[110:111]
	v_pk_mul_f32 v[0:1], v[0:1], v[118:119]
	s_waitcnt vmcnt(7)
	v_lshlrev_b32_e32 v48, 16, v210
	v_and_b32_e32 v49, 0xffff0000, v210
	v_lshlrev_b32_e32 v50, 16, v211
	v_and_b32_e32 v51, 0xffff0000, v211
	v_lshlrev_b32_e32 v56, 16, v212
	v_and_b32_e32 v57, 0xffff0000, v212
	v_lshlrev_b32_e32 v58, 16, v213
	v_and_b32_e32 v59, 0xffff0000, v213
	s_waitcnt vmcnt(7)
	v_pk_add_f32 v[48:49], v[48:49], v[238:239] op_sel_hi:[1,0] neg_lo:[0,1] neg_hi:[0,1]
	v_pk_add_f32 v[50:51], v[50:51], v[238:239] op_sel_hi:[1,0] neg_lo:[0,1] neg_hi:[0,1]
	v_pk_add_f32 v[56:57], v[56:57], v[238:239] op_sel_hi:[1,0] neg_lo:[0,1] neg_hi:[0,1]
	v_pk_add_f32 v[58:59], v[58:59], v[238:239] op_sel_hi:[1,0] neg_lo:[0,1] neg_hi:[0,1]
	v_pk_mul_f32 v[48:49], v[238:239], v[48:49] op_sel:[1,0]
	v_pk_mul_f32 v[50:51], v[238:239], v[50:51] op_sel:[1,0]
	v_pk_mul_f32 v[56:57], v[238:239], v[56:57] op_sel:[1,0]
	v_pk_mul_f32 v[58:59], v[238:239], v[58:59] op_sel:[1,0]
	v_pk_fma_f32 v[48:49], v[72:73], v[48:49], v[68:69]
	v_pk_fma_f32 v[50:51], v[74:75], v[50:51], v[70:71]
	v_pk_fma_f32 v[56:57], v[64:65], v[56:57], v[76:77]
	v_pk_fma_f32 v[58:59], v[66:67], v[58:59], v[78:79]
	v_pk_fma_f32 v[52:53], v[48:49], s[24:25], v[52:53] op_sel_hi:[1,0,1]
	v_pk_fma_f32 v[54:55], v[50:51], s[24:25], v[54:55] op_sel_hi:[1,0,1]
	v_pk_fma_f32 v[56:57], v[56:57], s[24:25], v[126:127] op_sel_hi:[1,0,1]
	v_pk_fma_f32 v[58:59], v[58:59], s[24:25], v[62:63] op_sel_hi:[1,0,1]
	v_cvt_pk_bf16_f32 v52, v52, v53
	v_cvt_pk_bf16_f32 v53, v54, v55
	v_cvt_pk_bf16_f32 v54, v56, v57
	v_cvt_pk_bf16_f32 v55, v58, v59
	v_pk_mul_f32 v[56:57], v[40:41], v[118:119]
	global_store_dwordx4 v[122:123], v[52:55], off offset:256
	s_waitcnt vmcnt(7)
	v_lshlrev_b32_e32 v40, 16, v214
	v_pk_mul_f32 v[54:55], v[42:43], v[110:111]
	v_and_b32_e32 v41, 0xffff0000, v214
	v_lshlrev_b32_e32 v42, 16, v215
	v_and_b32_e32 v43, 0xffff0000, v215
	v_lshlrev_b32_e32 v48, 16, v216
	v_and_b32_e32 v49, 0xffff0000, v216
	v_lshlrev_b32_e32 v50, 16, v217
	v_and_b32_e32 v51, 0xffff0000, v217
	s_waitcnt vmcnt(7)
	v_pk_add_f32 v[40:41], v[40:41], v[240:241] op_sel_hi:[1,0] neg_lo:[0,1] neg_hi:[0,1]
	v_pk_add_f32 v[42:43], v[42:43], v[240:241] op_sel_hi:[1,0] neg_lo:[0,1] neg_hi:[0,1]
	v_pk_add_f32 v[48:49], v[48:49], v[240:241] op_sel_hi:[1,0] neg_lo:[0,1] neg_hi:[0,1]
	v_pk_add_f32 v[50:51], v[50:51], v[240:241] op_sel_hi:[1,0] neg_lo:[0,1] neg_hi:[0,1]
	v_pk_mul_f32 v[40:41], v[240:241], v[40:41] op_sel:[1,0]
	v_pk_mul_f32 v[42:43], v[240:241], v[42:43] op_sel:[1,0]
	v_pk_mul_f32 v[48:49], v[240:241], v[48:49] op_sel:[1,0]
	v_pk_mul_f32 v[50:51], v[240:241], v[50:51] op_sel:[1,0]
	v_pk_fma_f32 v[40:41], v[72:73], v[40:41], v[68:69]
	v_pk_fma_f32 v[42:43], v[74:75], v[42:43], v[70:71]
	v_pk_fma_f32 v[48:49], v[64:65], v[48:49], v[76:77]
	v_pk_fma_f32 v[50:51], v[66:67], v[50:51], v[78:79]
	v_pk_fma_f32 v[44:45], v[40:41], s[24:25], v[44:45] op_sel_hi:[1,0,1]
	v_pk_fma_f32 v[46:47], v[42:43], s[24:25], v[46:47] op_sel_hi:[1,0,1]
	v_pk_fma_f32 v[48:49], v[48:49], s[24:25], v[56:57] op_sel_hi:[1,0,1]
	v_pk_fma_f32 v[50:51], v[50:51], s[24:25], v[54:55] op_sel_hi:[1,0,1]
	v_cvt_pk_bf16_f32 v44, v44, v45
	v_cvt_pk_bf16_f32 v45, v46, v47
	v_cvt_pk_bf16_f32 v46, v48, v49
	v_cvt_pk_bf16_f32 v47, v50, v51
	s_nop 0
	global_store_dwordx4 v[114:115], v[44:47], off offset:256
	s_waitcnt vmcnt(7)
	v_lshlrev_b32_e32 v48, 16, v220
	v_lshlrev_b32_e32 v46, 16, v218
	v_and_b32_e32 v47, 0xffff0000, v218
	v_lshlrev_b32_e32 v40, 16, v219
	v_and_b32_e32 v41, 0xffff0000, v219
	v_and_b32_e32 v49, 0xffff0000, v220
	v_lshlrev_b32_e32 v42, 16, v221
	v_and_b32_e32 v43, 0xffff0000, v221
	s_waitcnt vmcnt(7)
	v_pk_add_f32 v[46:47], v[46:47], v[242:243] op_sel_hi:[1,0] neg_lo:[0,1] neg_hi:[0,1]
	v_pk_add_f32 v[40:41], v[40:41], v[242:243] op_sel_hi:[1,0] neg_lo:[0,1] neg_hi:[0,1]
	v_pk_add_f32 v[48:49], v[48:49], v[242:243] op_sel_hi:[1,0] neg_lo:[0,1] neg_hi:[0,1]
	v_pk_add_f32 v[42:43], v[42:43], v[242:243] op_sel_hi:[1,0] neg_lo:[0,1] neg_hi:[0,1]
	v_pk_mul_f32 v[46:47], v[242:243], v[46:47] op_sel:[1,0]
	v_pk_mul_f32 v[40:41], v[242:243], v[40:41] op_sel:[1,0]
	v_pk_mul_f32 v[48:49], v[242:243], v[48:49] op_sel:[1,0]
	v_pk_mul_f32 v[42:43], v[242:243], v[42:43] op_sel:[1,0]
	v_pk_fma_f32 v[44:45], v[72:73], v[46:47], v[68:69]
	v_pk_fma_f32 v[40:41], v[74:75], v[40:41], v[70:71]
	v_pk_fma_f32 v[46:47], v[64:65], v[48:49], v[76:77]
	v_pk_fma_f32 v[42:43], v[66:67], v[42:43], v[78:79]
	v_pk_fma_f32 v[36:37], v[44:45], s[24:25], v[36:37] op_sel_hi:[1,0,1]
	v_pk_fma_f32 v[38:39], v[40:41], s[24:25], v[38:39] op_sel_hi:[1,0,1]
	v_pk_fma_f32 v[40:41], v[46:47], s[24:25], v[32:33] op_sel_hi:[1,0,1]
	v_pk_fma_f32 v[42:43], v[42:43], s[24:25], v[34:35] op_sel_hi:[1,0,1]
	v_cvt_pk_bf16_f32 v32, v36, v37
	v_cvt_pk_bf16_f32 v33, v38, v39
	v_cvt_pk_bf16_f32 v34, v40, v41
	v_cvt_pk_bf16_f32 v35, v42, v43
	global_store_dwordx4 v[106:107], v[32:35], off offset:256
	s_nop 0
	s_waitcnt vmcnt(7)
	v_lshlrev_b32_e32 v38, 16, v222
	v_and_b32_e32 v39, 0xffff0000, v222
	v_lshlrev_b32_e32 v32, 16, v223
	v_and_b32_e32 v33, 0xffff0000, v223
	v_lshlrev_b32_e32 v40, 16, v224
	v_and_b32_e32 v41, 0xffff0000, v224
	v_lshlrev_b32_e32 v34, 16, v225
	v_and_b32_e32 v35, 0xffff0000, v225
	s_waitcnt vmcnt(7)
	v_pk_add_f32 v[38:39], v[38:39], v[244:245] op_sel_hi:[1,0] neg_lo:[0,1] neg_hi:[0,1]
	v_pk_add_f32 v[32:33], v[32:33], v[244:245] op_sel_hi:[1,0] neg_lo:[0,1] neg_hi:[0,1]
	v_pk_add_f32 v[40:41], v[40:41], v[244:245] op_sel_hi:[1,0] neg_lo:[0,1] neg_hi:[0,1]
	v_pk_add_f32 v[34:35], v[34:35], v[244:245] op_sel_hi:[1,0] neg_lo:[0,1] neg_hi:[0,1]
	v_pk_mul_f32 v[38:39], v[244:245], v[38:39] op_sel:[1,0]
	v_pk_mul_f32 v[32:33], v[244:245], v[32:33] op_sel:[1,0]
	v_pk_mul_f32 v[40:41], v[244:245], v[40:41] op_sel:[1,0]
	v_pk_mul_f32 v[34:35], v[244:245], v[34:35] op_sel:[1,0]
	v_pk_fma_f32 v[36:37], v[72:73], v[38:39], v[68:69]
	v_pk_fma_f32 v[32:33], v[74:75], v[32:33], v[70:71]
	v_pk_fma_f32 v[38:39], v[64:65], v[40:41], v[76:77]
	v_pk_fma_f32 v[34:35], v[66:67], v[34:35], v[78:79]
	v_pk_fma_f32 v[28:29], v[36:37], s[24:25], v[28:29] op_sel_hi:[1,0,1]
	v_pk_fma_f32 v[30:31], v[32:33], s[24:25], v[30:31] op_sel_hi:[1,0,1]
	v_pk_fma_f32 v[32:33], v[38:39], s[24:25], v[24:25] op_sel_hi:[1,0,1]
	v_pk_fma_f32 v[34:35], v[34:35], s[24:25], v[26:27] op_sel_hi:[1,0,1]
	v_cvt_pk_bf16_f32 v24, v28, v29
	v_cvt_pk_bf16_f32 v25, v30, v31
	v_cvt_pk_bf16_f32 v26, v32, v33
	v_cvt_pk_bf16_f32 v27, v34, v35
	global_store_dwordx4 v[98:99], v[24:27], off offset:256
	s_nop 0
	s_waitcnt vmcnt(7)
	v_lshlrev_b32_e32 v30, 16, v226
	v_and_b32_e32 v31, 0xffff0000, v226
	v_lshlrev_b32_e32 v24, 16, v227
	v_and_b32_e32 v25, 0xffff0000, v227
	v_lshlrev_b32_e32 v32, 16, v228
	v_and_b32_e32 v33, 0xffff0000, v228
	v_lshlrev_b32_e32 v26, 16, v229
	v_and_b32_e32 v27, 0xffff0000, v229
	s_waitcnt vmcnt(7)
	v_pk_add_f32 v[30:31], v[30:31], v[246:247] op_sel_hi:[1,0] neg_lo:[0,1] neg_hi:[0,1]
	v_pk_add_f32 v[24:25], v[24:25], v[246:247] op_sel_hi:[1,0] neg_lo:[0,1] neg_hi:[0,1]
	v_pk_add_f32 v[32:33], v[32:33], v[246:247] op_sel_hi:[1,0] neg_lo:[0,1] neg_hi:[0,1]
	v_pk_add_f32 v[26:27], v[26:27], v[246:247] op_sel_hi:[1,0] neg_lo:[0,1] neg_hi:[0,1]
	v_pk_mul_f32 v[30:31], v[246:247], v[30:31] op_sel:[1,0]
	v_pk_mul_f32 v[24:25], v[246:247], v[24:25] op_sel:[1,0]
	v_pk_mul_f32 v[32:33], v[246:247], v[32:33] op_sel:[1,0]
	v_pk_mul_f32 v[26:27], v[246:247], v[26:27] op_sel:[1,0]
	v_pk_fma_f32 v[28:29], v[72:73], v[30:31], v[68:69]
	v_pk_fma_f32 v[24:25], v[74:75], v[24:25], v[70:71]
	v_pk_fma_f32 v[30:31], v[64:65], v[32:33], v[76:77]
	v_pk_fma_f32 v[26:27], v[66:67], v[26:27], v[78:79]
	v_pk_fma_f32 v[20:21], v[28:29], s[24:25], v[20:21] op_sel_hi:[1,0,1]
	v_pk_fma_f32 v[22:23], v[24:25], s[24:25], v[22:23] op_sel_hi:[1,0,1]
	v_pk_fma_f32 v[24:25], v[30:31], s[24:25], v[16:17] op_sel_hi:[1,0,1]
	v_pk_fma_f32 v[26:27], v[26:27], s[24:25], v[18:19] op_sel_hi:[1,0,1]
	v_cvt_pk_bf16_f32 v16, v20, v21
	v_cvt_pk_bf16_f32 v17, v22, v23
	v_cvt_pk_bf16_f32 v18, v24, v25
	v_cvt_pk_bf16_f32 v19, v26, v27
	global_store_dwordx4 v[90:91], v[16:19], off offset:256
	s_nop 0
	s_waitcnt vmcnt(7)
	v_lshlrev_b32_e32 v22, 16, v230
	v_and_b32_e32 v23, 0xffff0000, v230
	v_lshlrev_b32_e32 v16, 16, v231
	v_and_b32_e32 v17, 0xffff0000, v231
	v_lshlrev_b32_e32 v24, 16, v232
	v_and_b32_e32 v25, 0xffff0000, v232
	v_lshlrev_b32_e32 v18, 16, v233
	v_and_b32_e32 v19, 0xffff0000, v233
	s_waitcnt vmcnt(7)
	v_pk_add_f32 v[22:23], v[22:23], v[250:251] op_sel_hi:[1,0] neg_lo:[0,1] neg_hi:[0,1]
	v_pk_add_f32 v[16:17], v[16:17], v[250:251] op_sel_hi:[1,0] neg_lo:[0,1] neg_hi:[0,1]
	v_pk_add_f32 v[24:25], v[24:25], v[250:251] op_sel_hi:[1,0] neg_lo:[0,1] neg_hi:[0,1]
	v_pk_add_f32 v[18:19], v[18:19], v[250:251] op_sel_hi:[1,0] neg_lo:[0,1] neg_hi:[0,1]
	v_pk_mul_f32 v[22:23], v[250:251], v[22:23] op_sel:[1,0]
	v_pk_mul_f32 v[16:17], v[250:251], v[16:17] op_sel:[1,0]
	v_pk_mul_f32 v[24:25], v[250:251], v[24:25] op_sel:[1,0]
	v_pk_mul_f32 v[18:19], v[250:251], v[18:19] op_sel:[1,0]
	v_pk_fma_f32 v[20:21], v[72:73], v[22:23], v[68:69]
	v_pk_fma_f32 v[16:17], v[74:75], v[16:17], v[70:71]
	v_pk_fma_f32 v[22:23], v[64:65], v[24:25], v[76:77]
	v_pk_fma_f32 v[18:19], v[66:67], v[18:19], v[78:79]
	v_pk_fma_f32 v[12:13], v[20:21], s[24:25], v[12:13] op_sel_hi:[1,0,1]
	v_pk_fma_f32 v[14:15], v[16:17], s[24:25], v[14:15] op_sel_hi:[1,0,1]
	v_pk_fma_f32 v[16:17], v[22:23], s[24:25], v[8:9] op_sel_hi:[1,0,1]
	v_pk_fma_f32 v[18:19], v[18:19], s[24:25], v[10:11] op_sel_hi:[1,0,1]
	v_cvt_pk_bf16_f32 v8, v12, v13
	v_cvt_pk_bf16_f32 v9, v14, v15
	v_cvt_pk_bf16_f32 v10, v16, v17
	v_cvt_pk_bf16_f32 v11, v18, v19
	global_store_dwordx4 v[82:83], v[8:11], off offset:256
	s_nop 0
	s_waitcnt vmcnt(7)
	v_lshlrev_b32_e32 v14, 16, v234
	v_and_b32_e32 v15, 0xffff0000, v234
	v_lshlrev_b32_e32 v8, 16, v235
	v_and_b32_e32 v9, 0xffff0000, v235
	v_lshlrev_b32_e32 v16, 16, v236
	v_and_b32_e32 v17, 0xffff0000, v236
	v_lshlrev_b32_e32 v10, 16, v237
	v_and_b32_e32 v11, 0xffff0000, v237
	s_waitcnt vmcnt(7)
	v_pk_add_f32 v[14:15], v[14:15], v[252:253] op_sel_hi:[1,0] neg_lo:[0,1] neg_hi:[0,1]
	v_pk_add_f32 v[8:9], v[8:9], v[252:253] op_sel_hi:[1,0] neg_lo:[0,1] neg_hi:[0,1]
	v_pk_add_f32 v[16:17], v[16:17], v[252:253] op_sel_hi:[1,0] neg_lo:[0,1] neg_hi:[0,1]
	v_pk_add_f32 v[10:11], v[10:11], v[252:253] op_sel_hi:[1,0] neg_lo:[0,1] neg_hi:[0,1]
	v_pk_mul_f32 v[14:15], v[252:253], v[14:15] op_sel:[1,0]
	v_pk_mul_f32 v[8:9], v[252:253], v[8:9] op_sel:[1,0]
	v_pk_mul_f32 v[16:17], v[252:253], v[16:17] op_sel:[1,0]
	v_pk_mul_f32 v[10:11], v[252:253], v[10:11] op_sel:[1,0]
	v_pk_fma_f32 v[12:13], v[72:73], v[14:15], v[68:69]
	v_pk_fma_f32 v[8:9], v[74:75], v[8:9], v[70:71]
	v_pk_fma_f32 v[14:15], v[64:65], v[16:17], v[76:77]
	v_pk_fma_f32 v[10:11], v[66:67], v[10:11], v[78:79]
	v_pk_fma_f32 v[4:5], v[12:13], s[24:25], v[4:5] op_sel_hi:[1,0,1]
	v_pk_fma_f32 v[6:7], v[8:9], s[24:25], v[6:7] op_sel_hi:[1,0,1]
	v_pk_fma_f32 v[8:9], v[14:15], s[24:25], v[0:1] op_sel_hi:[1,0,1]
	v_pk_fma_f32 v[10:11], v[10:11], s[24:25], v[2:3] op_sel_hi:[1,0,1]
	v_cvt_pk_bf16_f32 v0, v4, v5
	v_cvt_pk_bf16_f32 v1, v6, v7
	v_cvt_pk_bf16_f32 v2, v8, v9
	v_cvt_pk_bf16_f32 v3, v10, v11
	global_store_dwordx4 v[84:85], v[0:3], off offset:256
	s_cbranch_vccnz .LBB0_2609
	s_andn2_b64 vcc, exec, s[8:9]
	s_cbranch_vccnz .LBB0_2608
	s_barrier
	s_branch .LBB0_2608
